# adds: all four GEMM mainloops issue LDS-DMA in saddr form (16 64-bit address VALU adds per trip removed)
# speedup vs baseline: 1.0396x; 1.0049x over previous
; #define STAGE(bufoff, gbase) do { _Pragma("unroll") for (int _i = 0; _i < 2; ++_i) \
;     __builtin_amdgcn_global_load_lds((const unsigned*)((const char*)(gbase) + voff[_i]), (__attribute__((address_space(3))) unsigned*)(lds + (bufoff) + ldsw + _i * 8192), 16, 0, 0); } while (0)
; #define LDA(dst, b, h) do { _Pragma("unroll") for (int m = 0; m < 4; ++m) _Pragma("unroll") for (int k = 0; k < 2; ++k) dst[m][k] = *(const __attribute__((address_space(3))) bf16x8*)(lds + SA(b, h) + aoff + m * 2048 + k * 1024); } while (0)
; #define LDB(dst, b, h) do { _Pragma("unroll") for (int n = 0; n < 2; ++n) _Pragma("unroll") for (int k = 0; k < 2; ++k) dst[n][k] = *(const __attribute__((address_space(3))) bf16x8*)(lds + SB(b, h) + boff + n * 2048 + k * 1024); } while (0)
; #define MMA(ai, bj, At_, Bt_) do { __builtin_amdgcn_s_setprio(1); \
;     _Pragma("unroll") for (int m = 0; m < 4; ++m) _Pragma("unroll") for (int n = 0; n < 2; ++n) _Pragma("unroll") for (int k = 0; k < 2; ++k) \
;       acc[ai][bj][m][n] = MFMA16(Bt_[n][k], At_[m][k], acc[ai][bj][m][n]); \
;     __builtin_amdgcn_s_setprio(0); } while (0)
; #define WAIT_V(n) asm volatile("s_waitcnt vmcnt(" #n ")" ::: "memory")
; #define WAIT_L(n) asm volatile("s_waitcnt lgkmcnt(" #n ")" ::: "memory")
; #define BAR __builtin_amdgcn_s_barrier()
; #define SCHED __builtin_amdgcn_sched_barrier(0)
; DI void gemm_phase(const GemmArgs& g, char* shm_c) {
;     ...
;     for (int t = 0; t < nt; t += 2) {
;       const bool last = t == nt - 2;
;       const char* a1 = cA + (size_t)(t + 1) * kstep;
;       const char* a2 = last ? nA : cA + (size_t)(t + 2) * kstep; const char* b2 = last ? nB : cB + (size_t)(t + 2) * kstep;
;       const char* a3 = a2 + kstep; const char* b3 = b2 + kstep;
;       LDB(B0, 0, 0); LDB(B1, 0, 1); SCHED; LDA(At, 0, 0); STAGE(SA(1, 1), a1 + hstep);
;       WAIT_V(8); WAIT_L(0); BAR; MMA(0, 0, At, B0); MMA(0, 1, At, B1); BAR; SCHED;
;       LDA(At, 0, 1); STAGE(SB(0, 0), b2); STAGE(SB(0, 1), b2 + hstep); STAGE(SA(0, 0), a2);
;       WAIT_V(8); WAIT_L(0); BAR; MMA(1, 0, At, B0); MMA(1, 1, At, B1); BAR; SCHED;
.LBB0_234:
	s_add_u32 s34, s8, 0x100
	s_addc_u32 s35, s9, 0
	s_add_i32 s2, 0, 0x10000
	s_cmp_eq_u32 s7, 12
	s_cselect_b32 s39, s29, s35
	s_cselect_b32 s38, s28, s34
	v_add_u32_e32 v138, s2, v142
	s_cselect_b32 s37, s31, s3
	s_cselect_b32 s36, s30, s1
	s_add_i32 s27, 0, 0x14000
	ds_read_b128 v[148:151], v138
	ds_read_b128 v[152:155], v138 offset:1024
	ds_read_b128 v[192:195], v138 offset:2048
	ds_read_b128 v[196:199], v138 offset:3072
	v_add_u32_e32 v138, s27, v142
	ds_read_b128 v[200:203], v138
	ds_read_b128 v[204:207], v138 offset:1024
	ds_read_b128 v[208:211], v138 offset:2048
	ds_read_b128 v[212:215], v138 offset:3072
	s_add_i32 s25, s49, 0
	s_add_i32 m0, s25, 0xc000
	ds_read_b128 v[216:219], v146
	ds_read_b128 v[220:223], v146 offset:1024
	ds_read_b128 v[224:227], v146 offset:2048
	ds_read_b128 v[228:231], v146 offset:3072
	ds_read_b128 v[232:235], v146 offset:4096
	ds_read_b128 v[236:239], v146 offset:5120
	ds_read_b128 v[240:243], v146 offset:6144
	ds_read_b128 v[244:247], v146 offset:7168
	global_load_lds_dwordx4 v134, s[8:9]
	s_add_i32 m0, s25, 0xe000
	s_nop 0
	global_load_lds_dwordx4 v136, s[8:9]
	s_waitcnt vmcnt(8)
	s_waitcnt lgkmcnt(0)
	s_barrier
	s_setprio 1
	s_waitcnt lgkmcnt(0)
	v_mfma_f32_16x16x32_bf16 v[126:129], v[148:151], v[216:219], v[126:129]
	v_mfma_f32_16x16x32_bf16 v[122:125], v[192:195], v[216:219], v[122:125]
	v_mfma_f32_16x16x32_bf16 v[110:113], v[148:151], v[224:227], v[110:113]
	v_mfma_f32_16x16x32_bf16 v[106:109], v[192:195], v[224:227], v[106:109]
	v_mfma_f32_16x16x32_bf16 v[94:97], v[148:151], v[232:235], v[94:97]
	v_mfma_f32_16x16x32_bf16 v[90:93], v[192:195], v[232:235], v[90:93]
	v_mfma_f32_16x16x32_bf16 v[78:81], v[148:151], v[240:243], v[78:81]
	v_mfma_f32_16x16x32_bf16 v[74:77], v[192:195], v[240:243], v[74:77]
	v_mfma_f32_16x16x32_bf16 v[126:129], v[152:155], v[220:223], v[126:129]
	v_mfma_f32_16x16x32_bf16 v[122:125], v[196:199], v[220:223], v[122:125]
	v_mfma_f32_16x16x32_bf16 v[110:113], v[152:155], v[228:231], v[110:113]
	v_mfma_f32_16x16x32_bf16 v[106:109], v[196:199], v[228:231], v[106:109]
	v_mfma_f32_16x16x32_bf16 v[94:97], v[152:155], v[236:239], v[94:97]
	v_mfma_f32_16x16x32_bf16 v[90:93], v[196:199], v[236:239], v[90:93]
	v_mfma_f32_16x16x32_bf16 v[78:81], v[152:155], v[244:247], v[78:81]
	v_mfma_f32_16x16x32_bf16 v[74:77], v[196:199], v[244:247], v[74:77]
	s_setprio 0
	s_setprio 1
	v_mfma_f32_16x16x32_bf16 v[118:121], v[200:203], v[216:219], v[118:121]
	v_mfma_f32_16x16x32_bf16 v[114:117], v[208:211], v[216:219], v[114:117]
	v_mfma_f32_16x16x32_bf16 v[102:105], v[200:203], v[224:227], v[102:105]
	v_mfma_f32_16x16x32_bf16 v[98:101], v[208:211], v[224:227], v[98:101]
	v_mfma_f32_16x16x32_bf16 v[86:89], v[200:203], v[232:235], v[86:89]
	v_mfma_f32_16x16x32_bf16 v[82:85], v[208:211], v[232:235], v[82:85]
	v_mfma_f32_16x16x32_bf16 v[70:73], v[200:203], v[240:243], v[70:73]
	v_mfma_f32_16x16x32_bf16 v[66:69], v[208:211], v[240:243], v[66:69]
	v_mfma_f32_16x16x32_bf16 v[118:121], v[204:207], v[220:223], v[118:121]
	v_mfma_f32_16x16x32_bf16 v[114:117], v[212:215], v[220:223], v[114:117]
	v_mfma_f32_16x16x32_bf16 v[102:105], v[204:207], v[228:231], v[102:105]
	v_mfma_f32_16x16x32_bf16 v[98:101], v[212:215], v[228:231], v[98:101]
	v_mfma_f32_16x16x32_bf16 v[86:89], v[204:207], v[236:239], v[86:89]
	v_mfma_f32_16x16x32_bf16 v[82:85], v[212:215], v[236:239], v[82:85]
	v_mfma_f32_16x16x32_bf16 v[70:73], v[204:207], v[244:247], v[70:73]
	v_mfma_f32_16x16x32_bf16 v[66:69], v[212:215], v[244:247], v[66:69]
	s_setprio 0
	s_barrier
	s_add_i32 s2, s2, s49
	s_mov_b32 m0, s2
	ds_read_b128 v[216:219], v146 offset:16384
	ds_read_b128 v[220:223], v146 offset:17408
	ds_read_b128 v[224:227], v146 offset:18432
	ds_read_b128 v[228:231], v146 offset:19456
	ds_read_b128 v[232:235], v146 offset:20480
	ds_read_b128 v[236:239], v146 offset:21504
	ds_read_b128 v[240:243], v146 offset:22528
	ds_read_b128 v[244:247], v146 offset:23552
	global_load_lds_dwordx4 v130, s[36:37]
	s_add_i32 m0, s2, 0x2000
	s_add_u32 s8, s36, 0x40000
	s_addc_u32 s9, s37, 0
	s_add_i32 s2, s27, s49
	global_load_lds_dwordx4 v132, s[36:37]
	s_mov_b32 m0, s2
	s_nop 0
	global_load_lds_dwordx4 v130, s[8:9]
	s_add_i32 m0, s2, 0x2000
	s_nop 0
	global_load_lds_dwordx4 v132, s[8:9]
	s_mov_b32 m0, s25
	s_nop 0
	global_load_lds_dwordx4 v130, s[38:39]
	s_add_i32 m0, s25, 0x2000
	s_nop 0
	global_load_lds_dwordx4 v132, s[38:39]
	s_waitcnt vmcnt(8)
	s_waitcnt lgkmcnt(0)
	s_barrier
	s_setprio 1
	s_waitcnt lgkmcnt(0)
	v_mfma_f32_16x16x32_bf16 v[62:65], v[148:151], v[216:219], v[62:65]
	v_mfma_f32_16x16x32_bf16 v[58:61], v[192:195], v[216:219], v[58:61]
	v_mfma_f32_16x16x32_bf16 v[46:49], v[148:151], v[224:227], v[46:49]
	v_mfma_f32_16x16x32_bf16 v[42:45], v[192:195], v[224:227], v[42:45]
	v_mfma_f32_16x16x32_bf16 v[22:25], v[148:151], v[232:235], v[22:25]
	v_mfma_f32_16x16x32_bf16 v[18:21], v[192:195], v[232:235], v[18:21]
	v_mfma_f32_16x16x32_bf16 v[6:9], v[148:151], v[240:243], v[6:9]
	v_mfma_f32_16x16x32_bf16 v[2:5], v[192:195], v[240:243], v[2:5]
	v_mfma_f32_16x16x32_bf16 v[62:65], v[152:155], v[220:223], v[62:65]
	v_mfma_f32_16x16x32_bf16 v[58:61], v[196:199], v[220:223], v[58:61]
	v_mfma_f32_16x16x32_bf16 v[46:49], v[152:155], v[228:231], v[46:49]
	v_mfma_f32_16x16x32_bf16 v[42:45], v[196:199], v[228:231], v[42:45]
	v_mfma_f32_16x16x32_bf16 v[22:25], v[152:155], v[236:239], v[22:25]
	v_mfma_f32_16x16x32_bf16 v[18:21], v[196:199], v[236:239], v[18:21]
	v_mfma_f32_16x16x32_bf16 v[6:9], v[152:155], v[244:247], v[6:9]
	v_mfma_f32_16x16x32_bf16 v[2:5], v[196:199], v[244:247], v[2:5]
	s_setprio 0
	s_setprio 1
	v_mfma_f32_16x16x32_bf16 v[54:57], v[200:203], v[216:219], v[54:57]
	v_mfma_f32_16x16x32_bf16 v[50:53], v[208:211], v[216:219], v[50:53]
	v_mfma_f32_16x16x32_bf16 v[38:41], v[200:203], v[224:227], v[38:41]
	v_mfma_f32_16x16x32_bf16 v[34:37], v[208:211], v[224:227], v[34:37]
	v_mfma_f32_16x16x32_bf16 v[30:33], v[200:203], v[232:235], v[30:33]
	v_mfma_f32_16x16x32_bf16 v[26:29], v[208:211], v[232:235], v[26:29]
	v_mfma_f32_16x16x32_bf16 v[14:17], v[200:203], v[240:243], v[14:17]
	v_mfma_f32_16x16x32_bf16 v[10:13], v[208:211], v[240:243], v[10:13]
	v_mfma_f32_16x16x32_bf16 v[54:57], v[204:207], v[220:223], v[54:57]
	v_mfma_f32_16x16x32_bf16 v[50:53], v[212:215], v[220:223], v[50:53]
	v_mfma_f32_16x16x32_bf16 v[38:41], v[204:207], v[228:231], v[38:41]
	v_mfma_f32_16x16x32_bf16 v[34:37], v[212:215], v[228:231], v[34:37]
	v_mfma_f32_16x16x32_bf16 v[30:33], v[204:207], v[236:239], v[30:33]
	v_mfma_f32_16x16x32_bf16 v[26:29], v[212:215], v[236:239], v[26:29]
	v_mfma_f32_16x16x32_bf16 v[14:17], v[204:207], v[244:247], v[14:17]
	v_mfma_f32_16x16x32_bf16 v[10:13], v[212:215], v[244:247], v[10:13]
	s_setprio 0
	s_barrier
; #define STAGE(bufoff, gbase) do { _Pragma("unroll") for (int _i = 0; _i < 2; ++_i) \
;     __builtin_amdgcn_global_load_lds((const unsigned*)((const char*)(gbase) + voff[_i]), (__attribute__((address_space(3))) unsigned*)(lds + (bufoff) + ldsw + _i * 8192), 16, 0, 0); } while (0)
; #define LDA(dst, b, h) do { _Pragma("unroll") for (int m = 0; m < 4; ++m) _Pragma("unroll") for (int k = 0; k < 2; ++k) dst[m][k] = *(const __attribute__((address_space(3))) bf16x8*)(lds + SA(b, h) + aoff + m * 2048 + k * 1024); } while (0)
; #define LDB(dst, b, h) do { _Pragma("unroll") for (int n = 0; n < 2; ++n) _Pragma("unroll") for (int k = 0; k < 2; ++k) dst[n][k] = *(const __attribute__((address_space(3))) bf16x8*)(lds + SB(b, h) + boff + n * 2048 + k * 1024); } while (0)
; #define MMA(ai, bj, At_, Bt_) do { __builtin_amdgcn_s_setprio(1); \
;     _Pragma("unroll") for (int m = 0; m < 4; ++m) _Pragma("unroll") for (int n = 0; n < 2; ++n) _Pragma("unroll") for (int k = 0; k < 2; ++k) \
;       acc[ai][bj][m][n] = MFMA16(Bt_[n][k], At_[m][k], acc[ai][bj][m][n]); \
;     __builtin_amdgcn_s_setprio(0); } while (0)
; #define WAIT_V(n) asm volatile("s_waitcnt vmcnt(" #n ")" ::: "memory")
; #define WAIT_L(n) asm volatile("s_waitcnt lgkmcnt(" #n ")" ::: "memory")
; #define BAR __builtin_amdgcn_s_barrier()
; #define SCHED __builtin_amdgcn_sched_barrier(0)
; DI void gemm_phase(const GemmArgs& g, char* shm_c) {
;     ...
;       LDB(B0, 1, 0); LDB(B1, 1, 1); SCHED; LDA(At, 1, 0); STAGE(SA(0, 1), a2 + hstep);
;       WAIT_V(8); WAIT_L(0); BAR; MMA(0, 0, At, B0); MMA(0, 1, At, B1); BAR; SCHED;
;       LDA(At, 1, 1); STAGE(SB(1, 0), b3); STAGE(SB(1, 1), b3 + hstep); STAGE(SA(1, 0), a3);
;       WAIT_V(8); WAIT_L(0); BAR; MMA(1, 0, At, B0); MMA(1, 1, At, B1); BAR; SCHED;
;     }
	s_add_i32 s2, 0, 0x18000
	v_add_u32_e32 v147, s2, v142
	s_add_i32 s27, 0, 0x1c000
	ds_read_b128 v[148:151], v147
	ds_read_b128 v[152:155], v147 offset:1024
	ds_read_b128 v[192:195], v147 offset:2048
	ds_read_b128 v[196:199], v147 offset:3072
	v_add_u32_e32 v147, s27, v142
	ds_read_b128 v[200:203], v147
	ds_read_b128 v[204:207], v147 offset:1024
	ds_read_b128 v[208:211], v147 offset:2048
	ds_read_b128 v[212:215], v147 offset:3072
	s_add_u32 s8, s38, 0x40000
	s_addc_u32 s9, s39, 0
	s_add_i32 m0, s25, 0x4000
	ds_read_b128 v[216:219], v146 offset:32768
	ds_read_b128 v[220:223], v146 offset:33792
	ds_read_b128 v[224:227], v146 offset:34816
	ds_read_b128 v[228:231], v146 offset:35840
	ds_read_b128 v[232:235], v146 offset:36864
	ds_read_b128 v[236:239], v146 offset:37888
	ds_read_b128 v[240:243], v146 offset:38912
	ds_read_b128 v[244:247], v146 offset:39936
	global_load_lds_dwordx4 v130, s[8:9]
	s_add_i32 m0, s25, 0x6000
	s_nop 0
	global_load_lds_dwordx4 v132, s[8:9]
	s_waitcnt vmcnt(8)
	s_waitcnt lgkmcnt(0)
	s_barrier
	s_setprio 1
	s_waitcnt lgkmcnt(0)
	v_mfma_f32_16x16x32_bf16 v[126:129], v[148:151], v[216:219], v[126:129]
	v_mfma_f32_16x16x32_bf16 v[122:125], v[192:195], v[216:219], v[122:125]
	v_mfma_f32_16x16x32_bf16 v[110:113], v[148:151], v[224:227], v[110:113]
	v_mfma_f32_16x16x32_bf16 v[106:109], v[192:195], v[224:227], v[106:109]
	v_mfma_f32_16x16x32_bf16 v[94:97], v[148:151], v[232:235], v[94:97]
	v_mfma_f32_16x16x32_bf16 v[90:93], v[192:195], v[232:235], v[90:93]
	v_mfma_f32_16x16x32_bf16 v[78:81], v[148:151], v[240:243], v[78:81]
	v_mfma_f32_16x16x32_bf16 v[74:77], v[192:195], v[240:243], v[74:77]
	v_mfma_f32_16x16x32_bf16 v[126:129], v[152:155], v[220:223], v[126:129]
	v_mfma_f32_16x16x32_bf16 v[122:125], v[196:199], v[220:223], v[122:125]
	v_mfma_f32_16x16x32_bf16 v[110:113], v[152:155], v[228:231], v[110:113]
	v_mfma_f32_16x16x32_bf16 v[106:109], v[196:199], v[228:231], v[106:109]
	v_mfma_f32_16x16x32_bf16 v[94:97], v[152:155], v[236:239], v[94:97]
	v_mfma_f32_16x16x32_bf16 v[90:93], v[196:199], v[236:239], v[90:93]
	v_mfma_f32_16x16x32_bf16 v[78:81], v[152:155], v[244:247], v[78:81]
	v_mfma_f32_16x16x32_bf16 v[74:77], v[196:199], v[244:247], v[74:77]
	s_setprio 0
	s_setprio 1
	v_mfma_f32_16x16x32_bf16 v[118:121], v[200:203], v[216:219], v[118:121]
	v_mfma_f32_16x16x32_bf16 v[114:117], v[208:211], v[216:219], v[114:117]
	v_mfma_f32_16x16x32_bf16 v[102:105], v[200:203], v[224:227], v[102:105]
	v_mfma_f32_16x16x32_bf16 v[98:101], v[208:211], v[224:227], v[98:101]
	v_mfma_f32_16x16x32_bf16 v[86:89], v[200:203], v[232:235], v[86:89]
	v_mfma_f32_16x16x32_bf16 v[82:85], v[208:211], v[232:235], v[82:85]
	v_mfma_f32_16x16x32_bf16 v[70:73], v[200:203], v[240:243], v[70:73]
	v_mfma_f32_16x16x32_bf16 v[66:69], v[208:211], v[240:243], v[66:69]
	v_mfma_f32_16x16x32_bf16 v[118:121], v[204:207], v[220:223], v[118:121]
	v_mfma_f32_16x16x32_bf16 v[114:117], v[212:215], v[220:223], v[114:117]
	v_mfma_f32_16x16x32_bf16 v[102:105], v[204:207], v[228:231], v[102:105]
	v_mfma_f32_16x16x32_bf16 v[98:101], v[212:215], v[228:231], v[98:101]
	v_mfma_f32_16x16x32_bf16 v[86:89], v[204:207], v[236:239], v[86:89]
	v_mfma_f32_16x16x32_bf16 v[82:85], v[212:215], v[236:239], v[82:85]
	v_mfma_f32_16x16x32_bf16 v[70:73], v[204:207], v[244:247], v[70:73]
	v_mfma_f32_16x16x32_bf16 v[66:69], v[212:215], v[244:247], v[66:69]
	s_setprio 0
	s_barrier
	s_add_i32 s2, s2, s49
	s_add_i32 m0, s2, 0xffffff80
	ds_read_b128 v[216:219], v146 offset:49152
	ds_read_b128 v[220:223], v146 offset:50176
	ds_read_b128 v[224:227], v146 offset:51200
	ds_read_b128 v[228:231], v146 offset:52224
	ds_read_b128 v[232:235], v146 offset:53248
	ds_read_b128 v[236:239], v146 offset:54272
	ds_read_b128 v[240:243], v146 offset:55296
	ds_read_b128 v[244:247], v146 offset:56320
	global_load_lds_dwordx4 v130, s[36:37] offset:128
	s_add_i32 m0, s2, 0x1f80
	s_add_u32 s8, s36, 0x40080
	s_addc_u32 s9, s37, 0
	s_add_i32 s2, s27, s49
	global_load_lds_dwordx4 v132, s[36:37] offset:128
	s_mov_b32 m0, s2
	s_nop 0
	global_load_lds_dwordx4 v130, s[8:9]
	s_add_i32 m0, s2, 0x2000
	s_nop 0
	global_load_lds_dwordx4 v132, s[8:9]
	s_add_i32 m0, s25, 0x7f80
	s_nop 0
	global_load_lds_dwordx4 v130, s[38:39] offset:128
	s_add_i32 m0, s25, 0x9f80
	s_nop 0
	global_load_lds_dwordx4 v132, s[38:39] offset:128
	s_waitcnt vmcnt(8)
	s_waitcnt lgkmcnt(0)
	s_barrier
	s_setprio 1
	s_waitcnt lgkmcnt(0)
	v_mfma_f32_16x16x32_bf16 v[62:65], v[148:151], v[216:219], v[62:65]
	v_mfma_f32_16x16x32_bf16 v[58:61], v[192:195], v[216:219], v[58:61]
	v_mfma_f32_16x16x32_bf16 v[46:49], v[148:151], v[224:227], v[46:49]
	v_mfma_f32_16x16x32_bf16 v[42:45], v[192:195], v[224:227], v[42:45]
	v_mfma_f32_16x16x32_bf16 v[22:25], v[148:151], v[232:235], v[22:25]
	v_mfma_f32_16x16x32_bf16 v[18:21], v[192:195], v[232:235], v[18:21]
	v_mfma_f32_16x16x32_bf16 v[6:9], v[148:151], v[240:243], v[6:9]
	v_mfma_f32_16x16x32_bf16 v[2:5], v[192:195], v[240:243], v[2:5]
	v_mfma_f32_16x16x32_bf16 v[62:65], v[152:155], v[220:223], v[62:65]
	v_mfma_f32_16x16x32_bf16 v[58:61], v[196:199], v[220:223], v[58:61]
	v_mfma_f32_16x16x32_bf16 v[46:49], v[152:155], v[228:231], v[46:49]
	v_mfma_f32_16x16x32_bf16 v[42:45], v[196:199], v[228:231], v[42:45]
	v_mfma_f32_16x16x32_bf16 v[22:25], v[152:155], v[236:239], v[22:25]
	v_mfma_f32_16x16x32_bf16 v[18:21], v[196:199], v[236:239], v[18:21]
	v_mfma_f32_16x16x32_bf16 v[6:9], v[152:155], v[244:247], v[6:9]
	v_mfma_f32_16x16x32_bf16 v[2:5], v[196:199], v[244:247], v[2:5]
	s_setprio 0
	s_setprio 1
	v_mfma_f32_16x16x32_bf16 v[54:57], v[200:203], v[216:219], v[54:57]
	v_mfma_f32_16x16x32_bf16 v[50:53], v[208:211], v[216:219], v[50:53]
	v_mfma_f32_16x16x32_bf16 v[38:41], v[200:203], v[224:227], v[38:41]
	v_mfma_f32_16x16x32_bf16 v[34:37], v[208:211], v[224:227], v[34:37]
	v_mfma_f32_16x16x32_bf16 v[30:33], v[200:203], v[232:235], v[30:33]
	v_mfma_f32_16x16x32_bf16 v[26:29], v[208:211], v[232:235], v[26:29]
	v_mfma_f32_16x16x32_bf16 v[14:17], v[200:203], v[240:243], v[14:17]
	v_mfma_f32_16x16x32_bf16 v[10:13], v[208:211], v[240:243], v[10:13]
	v_mfma_f32_16x16x32_bf16 v[54:57], v[204:207], v[220:223], v[54:57]
	v_mfma_f32_16x16x32_bf16 v[50:53], v[212:215], v[220:223], v[50:53]
	v_mfma_f32_16x16x32_bf16 v[38:41], v[204:207], v[228:231], v[38:41]
	v_mfma_f32_16x16x32_bf16 v[34:37], v[212:215], v[228:231], v[34:37]
	v_mfma_f32_16x16x32_bf16 v[30:33], v[204:207], v[236:239], v[30:33]
	v_mfma_f32_16x16x32_bf16 v[26:29], v[212:215], v[236:239], v[26:29]
	v_mfma_f32_16x16x32_bf16 v[14:17], v[204:207], v[244:247], v[14:17]
	v_mfma_f32_16x16x32_bf16 v[10:13], v[212:215], v[244:247], v[10:13]
	s_setprio 0
	s_barrier
	s_add_i32 s7, s7, 2
	s_add_u32 s1, s1, 0x100
	s_addc_u32 s3, s3, 0
	s_cmp_gt_u32 s7, 13
	s_mov_b64 s[8:9], s[34:35]
	s_cbranch_scc0 .LBB0_234
	s_and_b64 vcc, exec, s[16:17]
	s_cbranch_vccz .LBB0_237
	s_barrier

; #define STAGE(bufoff, gbase) do { _Pragma("unroll") for (int _i = 0; _i < 2; ++_i) \
;     __builtin_amdgcn_global_load_lds((const unsigned*)((const char*)(gbase) + voff[_i]), (__attribute__((address_space(3))) unsigned*)(lds + (bufoff) + ldsw + _i * 8192), 16, 0, 0); } while (0)
; #define LDA(dst, b, h) do { _Pragma("unroll") for (int m = 0; m < 4; ++m) _Pragma("unroll") for (int k = 0; k < 2; ++k) dst[m][k] = *(const __attribute__((address_space(3))) bf16x8*)(lds + SA(b, h) + aoff + m * 2048 + k * 1024); } while (0)
; #define LDB(dst, b, h) do { _Pragma("unroll") for (int n = 0; n < 2; ++n) _Pragma("unroll") for (int k = 0; k < 2; ++k) dst[n][k] = *(const __attribute__((address_space(3))) bf16x8*)(lds + SB(b, h) + boff + n * 2048 + k * 1024); } while (0)
; #define MMA(ai, bj, At_, Bt_) do { __builtin_amdgcn_s_setprio(1); \
;     _Pragma("unroll") for (int m = 0; m < 4; ++m) _Pragma("unroll") for (int n = 0; n < 2; ++n) _Pragma("unroll") for (int k = 0; k < 2; ++k) \
;       acc[ai][bj][m][n] = MFMA16(Bt_[n][k], At_[m][k], acc[ai][bj][m][n]); \
;     __builtin_amdgcn_s_setprio(0); } while (0)
; #define WAIT_V(n) asm volatile("s_waitcnt vmcnt(" #n ")" ::: "memory")
; #define WAIT_L(n) asm volatile("s_waitcnt lgkmcnt(" #n ")" ::: "memory")
; #define BAR __builtin_amdgcn_s_barrier()
; #define SCHED __builtin_amdgcn_sched_barrier(0)
; DI void gemm_phase(const GemmArgs& g, char* shm_c) {
;     ...
;     for (int t = 0; t < nt; t += 2) {
;       const bool last = t == nt - 2;
;       const char* a1 = cA + (size_t)(t + 1) * kstep;
;       const char* a2 = last ? nA : cA + (size_t)(t + 2) * kstep; const char* b2 = last ? nB : cB + (size_t)(t + 2) * kstep;
;       const char* a3 = a2 + kstep; const char* b3 = b2 + kstep;
;       LDB(B0, 0, 0); LDB(B1, 0, 1); SCHED; LDA(At, 0, 0); STAGE(SA(1, 1), a1 + hstep);
;       WAIT_V(8); WAIT_L(0); BAR; MMA(0, 0, At, B0); MMA(0, 1, At, B1); BAR; SCHED;
;       LDA(At, 0, 1); STAGE(SB(0, 0), b2); STAGE(SB(0, 1), b2 + hstep); STAGE(SA(0, 0), a2);
;       WAIT_V(8); WAIT_L(0); BAR; MMA(1, 0, At, B0); MMA(1, 1, At, B1); BAR; SCHED;
.LBB0_879:
	s_add_u32 s56, s48, 0x100
	s_addc_u32 s57, s49, 0
	s_add_i32 s2, 0, 0x10000
	s_cmp_eq_u32 s39, 12
	s_cselect_b32 s61, s35, s57
	s_cselect_b32 s60, s34, s56
	s_cselect_b32 s59, s37, s31
	s_cselect_b32 s58, s36, s29
	s_add_i32 s41, 0, 0x14000
	v_add_u32_e32 v142, s2, v195
	v_add_u32_e32 v156, s41, v195
	ds_read_b128 v[130:133], v142
	ds_read_b128 v[134:137], v142 offset:1024
	ds_read_b128 v[138:141], v142 offset:2048
	ds_read_b128 v[142:145], v142 offset:3072
	ds_read_b128 v[198:201], v156
	ds_read_b128 v[202:205], v156 offset:1024
	ds_read_b128 v[206:209], v156 offset:2048
	ds_read_b128 v[210:213], v156 offset:3072
	s_add_i32 s51, s3, 0
	s_add_i32 m0, s51, 0xc000
	ds_read_b128 v[214:217], v196
	ds_read_b128 v[218:221], v196 offset:1024
	ds_read_b128 v[222:225], v196 offset:2048
	ds_read_b128 v[226:229], v196 offset:3072
	ds_read_b128 v[230:233], v196 offset:4096
	ds_read_b128 v[234:237], v196 offset:5120
	ds_read_b128 v[238:241], v196 offset:6144
	ds_read_b128 v[242:245], v196 offset:7168
	global_load_lds_dwordx4 v152, s[48:49]
	s_add_i32 m0, s51, 0xe000
	s_nop 0
	global_load_lds_dwordx4 v154, s[48:49]
	s_waitcnt vmcnt(8)
	s_waitcnt lgkmcnt(0)
	s_barrier
	s_setprio 1
	s_waitcnt lgkmcnt(0)
	v_mfma_f32_16x16x32_bf16 v[126:129], v[130:133], v[214:217], v[126:129]
	v_mfma_f32_16x16x32_bf16 v[122:125], v[138:141], v[214:217], v[122:125]
	v_mfma_f32_16x16x32_bf16 v[114:117], v[130:133], v[222:225], v[114:117]
	v_mfma_f32_16x16x32_bf16 v[110:113], v[138:141], v[222:225], v[110:113]
	v_mfma_f32_16x16x32_bf16 v[98:101], v[130:133], v[230:233], v[98:101]
	v_mfma_f32_16x16x32_bf16 v[94:97], v[138:141], v[230:233], v[94:97]
	v_mfma_f32_16x16x32_bf16 v[82:85], v[130:133], v[238:241], v[82:85]
	v_mfma_f32_16x16x32_bf16 v[78:81], v[138:141], v[238:241], v[78:81]
	v_mfma_f32_16x16x32_bf16 v[126:129], v[134:137], v[218:221], v[126:129]
	v_mfma_f32_16x16x32_bf16 v[122:125], v[142:145], v[218:221], v[122:125]
	v_mfma_f32_16x16x32_bf16 v[114:117], v[134:137], v[226:229], v[114:117]
	v_mfma_f32_16x16x32_bf16 v[110:113], v[142:145], v[226:229], v[110:113]
	v_mfma_f32_16x16x32_bf16 v[98:101], v[134:137], v[234:237], v[98:101]
	v_mfma_f32_16x16x32_bf16 v[94:97], v[142:145], v[234:237], v[94:97]
	v_mfma_f32_16x16x32_bf16 v[82:85], v[134:137], v[242:245], v[82:85]
	v_mfma_f32_16x16x32_bf16 v[78:81], v[142:145], v[242:245], v[78:81]
	s_setprio 0
	s_setprio 1
	v_mfma_f32_16x16x32_bf16 v[118:121], v[198:201], v[214:217], v[118:121]
	v_mfma_f32_16x16x32_bf16 v[106:109], v[206:209], v[214:217], v[106:109]
	v_mfma_f32_16x16x32_bf16 v[102:105], v[198:201], v[222:225], v[102:105]
	v_mfma_f32_16x16x32_bf16 v[90:93], v[206:209], v[222:225], v[90:93]
	v_mfma_f32_16x16x32_bf16 v[86:89], v[198:201], v[230:233], v[86:89]
	v_mfma_f32_16x16x32_bf16 v[74:77], v[206:209], v[230:233], v[74:77]
	v_mfma_f32_16x16x32_bf16 v[70:73], v[198:201], v[238:241], v[70:73]
	v_mfma_f32_16x16x32_bf16 v[66:69], v[206:209], v[238:241], v[66:69]
	v_mfma_f32_16x16x32_bf16 v[118:121], v[202:205], v[218:221], v[118:121]
	v_mfma_f32_16x16x32_bf16 v[106:109], v[210:213], v[218:221], v[106:109]
	v_mfma_f32_16x16x32_bf16 v[102:105], v[202:205], v[226:229], v[102:105]
	v_mfma_f32_16x16x32_bf16 v[90:93], v[210:213], v[226:229], v[90:93]
	v_mfma_f32_16x16x32_bf16 v[86:89], v[202:205], v[234:237], v[86:89]
	v_mfma_f32_16x16x32_bf16 v[74:77], v[210:213], v[234:237], v[74:77]
	v_mfma_f32_16x16x32_bf16 v[70:73], v[202:205], v[242:245], v[70:73]
	v_mfma_f32_16x16x32_bf16 v[66:69], v[210:213], v[242:245], v[66:69]
	s_setprio 0
	s_barrier
	s_add_i32 s2, s2, s3
	s_mov_b32 m0, s2
	ds_read_b128 v[214:217], v196 offset:16384
	ds_read_b128 v[218:221], v196 offset:17408
	ds_read_b128 v[222:225], v196 offset:18432
	ds_read_b128 v[226:229], v196 offset:19456
	ds_read_b128 v[230:233], v196 offset:20480
	ds_read_b128 v[234:237], v196 offset:21504
	ds_read_b128 v[238:241], v196 offset:22528
	ds_read_b128 v[242:245], v196 offset:23552
	global_load_lds_dwordx4 v148, s[58:59]
	s_add_i32 m0, s2, 0x2000
	s_add_u32 s48, s58, 0x40000
	s_addc_u32 s49, s59, 0
	s_add_i32 s2, s41, s3
	global_load_lds_dwordx4 v150, s[58:59]
	s_mov_b32 m0, s2
	s_nop 0
	global_load_lds_dwordx4 v148, s[48:49]
	s_add_i32 m0, s2, 0x2000
	s_nop 0
	global_load_lds_dwordx4 v150, s[48:49]
	s_mov_b32 m0, s51
	s_nop 0
	global_load_lds_dwordx4 v148, s[60:61]
	s_add_i32 m0, s51, 0x2000
	s_nop 0
	global_load_lds_dwordx4 v150, s[60:61]
	s_waitcnt vmcnt(8)
	s_waitcnt lgkmcnt(0)
	s_barrier
	s_setprio 1
	s_waitcnt lgkmcnt(0)
	v_mfma_f32_16x16x32_bf16 v[62:65], v[130:133], v[214:217], v[62:65]
	v_mfma_f32_16x16x32_bf16 v[58:61], v[138:141], v[214:217], v[58:61]
	v_mfma_f32_16x16x32_bf16 v[50:53], v[130:133], v[222:225], v[50:53]
	v_mfma_f32_16x16x32_bf16 v[42:45], v[138:141], v[222:225], v[42:45]
	v_mfma_f32_16x16x32_bf16 v[22:25], v[130:133], v[230:233], v[22:25]
	v_mfma_f32_16x16x32_bf16 v[18:21], v[138:141], v[230:233], v[18:21]
	v_mfma_f32_16x16x32_bf16 v[6:9], v[130:133], v[238:241], v[6:9]
	v_mfma_f32_16x16x32_bf16 v[2:5], v[138:141], v[238:241], v[2:5]
	v_mfma_f32_16x16x32_bf16 v[62:65], v[134:137], v[218:221], v[62:65]
	v_mfma_f32_16x16x32_bf16 v[58:61], v[142:145], v[218:221], v[58:61]
	v_mfma_f32_16x16x32_bf16 v[50:53], v[134:137], v[226:229], v[50:53]
	v_mfma_f32_16x16x32_bf16 v[42:45], v[142:145], v[226:229], v[42:45]
	v_mfma_f32_16x16x32_bf16 v[22:25], v[134:137], v[234:237], v[22:25]
	v_mfma_f32_16x16x32_bf16 v[18:21], v[142:145], v[234:237], v[18:21]
	v_mfma_f32_16x16x32_bf16 v[6:9], v[134:137], v[242:245], v[6:9]
	v_mfma_f32_16x16x32_bf16 v[2:5], v[142:145], v[242:245], v[2:5]
	s_setprio 0
	s_setprio 1
	v_mfma_f32_16x16x32_bf16 v[54:57], v[198:201], v[214:217], v[54:57]
	v_mfma_f32_16x16x32_bf16 v[38:41], v[206:209], v[214:217], v[38:41]
	v_mfma_f32_16x16x32_bf16 v[30:33], v[198:201], v[222:225], v[30:33]
	v_mfma_f32_16x16x32_bf16 v[10:13], v[206:209], v[222:225], v[10:13]
	v_mfma_f32_16x16x32_bf16 v[46:49], v[198:201], v[230:233], v[46:49]
	v_mfma_f32_16x16x32_bf16 v[34:37], v[206:209], v[230:233], v[34:37]
	v_mfma_f32_16x16x32_bf16 v[26:29], v[198:201], v[238:241], v[26:29]
	v_mfma_f32_16x16x32_bf16 v[14:17], v[206:209], v[238:241], v[14:17]
	v_mfma_f32_16x16x32_bf16 v[54:57], v[202:205], v[218:221], v[54:57]
	v_mfma_f32_16x16x32_bf16 v[38:41], v[210:213], v[218:221], v[38:41]
	v_mfma_f32_16x16x32_bf16 v[30:33], v[202:205], v[226:229], v[30:33]
	v_mfma_f32_16x16x32_bf16 v[10:13], v[210:213], v[226:229], v[10:13]
	v_mfma_f32_16x16x32_bf16 v[46:49], v[202:205], v[234:237], v[46:49]
	v_mfma_f32_16x16x32_bf16 v[34:37], v[210:213], v[234:237], v[34:37]
	v_mfma_f32_16x16x32_bf16 v[26:29], v[202:205], v[242:245], v[26:29]
	v_mfma_f32_16x16x32_bf16 v[14:17], v[210:213], v[242:245], v[14:17]
	s_setprio 0
	s_barrier
; #define STAGE(bufoff, gbase) do { _Pragma("unroll") for (int _i = 0; _i < 2; ++_i) \
;     __builtin_amdgcn_global_load_lds((const unsigned*)((const char*)(gbase) + voff[_i]), (__attribute__((address_space(3))) unsigned*)(lds + (bufoff) + ldsw + _i * 8192), 16, 0, 0); } while (0)
; #define LDA(dst, b, h) do { _Pragma("unroll") for (int m = 0; m < 4; ++m) _Pragma("unroll") for (int k = 0; k < 2; ++k) dst[m][k] = *(const __attribute__((address_space(3))) bf16x8*)(lds + SA(b, h) + aoff + m * 2048 + k * 1024); } while (0)
; #define LDB(dst, b, h) do { _Pragma("unroll") for (int n = 0; n < 2; ++n) _Pragma("unroll") for (int k = 0; k < 2; ++k) dst[n][k] = *(const __attribute__((address_space(3))) bf16x8*)(lds + SB(b, h) + boff + n * 2048 + k * 1024); } while (0)
; #define MMA(ai, bj, At_, Bt_) do { __builtin_amdgcn_s_setprio(1); \
;     _Pragma("unroll") for (int m = 0; m < 4; ++m) _Pragma("unroll") for (int n = 0; n < 2; ++n) _Pragma("unroll") for (int k = 0; k < 2; ++k) \
;       acc[ai][bj][m][n] = MFMA16(Bt_[n][k], At_[m][k], acc[ai][bj][m][n]); \
;     __builtin_amdgcn_s_setprio(0); } while (0)
; #define WAIT_V(n) asm volatile("s_waitcnt vmcnt(" #n ")" ::: "memory")
; #define WAIT_L(n) asm volatile("s_waitcnt lgkmcnt(" #n ")" ::: "memory")
; #define BAR __builtin_amdgcn_s_barrier()
; #define SCHED __builtin_amdgcn_sched_barrier(0)
; DI void gemm_phase(const GemmArgs& g, char* shm_c) {
;     ...
;       LDB(B0, 1, 0); LDB(B1, 1, 1); SCHED; LDA(At, 1, 0); STAGE(SA(0, 1), a2 + hstep);
;       WAIT_V(8); WAIT_L(0); BAR; MMA(0, 0, At, B0); MMA(0, 1, At, B1); BAR; SCHED;
;       LDA(At, 1, 1); STAGE(SB(1, 0), b3); STAGE(SB(1, 1), b3 + hstep); STAGE(SA(1, 0), a3);
;       WAIT_V(8); WAIT_L(0); BAR; MMA(1, 0, At, B0); MMA(1, 1, At, B1); BAR; SCHED;
;     }
	s_add_i32 s2, 0, 0x18000
	s_add_i32 s41, 0, 0x1c000
	v_add_u32_e32 v142, s2, v195
	v_add_u32_e32 v197, s41, v195
	ds_read_b128 v[130:133], v142
	ds_read_b128 v[134:137], v142 offset:1024
	ds_read_b128 v[138:141], v142 offset:2048
	ds_read_b128 v[142:145], v142 offset:3072
	ds_read_b128 v[198:201], v197
	ds_read_b128 v[202:205], v197 offset:1024
	ds_read_b128 v[206:209], v197 offset:2048
	ds_read_b128 v[210:213], v197 offset:3072
	s_add_u32 s48, s60, 0x40000
	s_addc_u32 s49, s61, 0
	s_add_i32 m0, s51, 0x4000
	ds_read_b128 v[214:217], v196 offset:32768
	ds_read_b128 v[218:221], v196 offset:33792
	ds_read_b128 v[222:225], v196 offset:34816
	ds_read_b128 v[226:229], v196 offset:35840
	ds_read_b128 v[230:233], v196 offset:36864
	ds_read_b128 v[234:237], v196 offset:37888
	ds_read_b128 v[238:241], v196 offset:38912
	ds_read_b128 v[242:245], v196 offset:39936
	global_load_lds_dwordx4 v148, s[48:49]
	s_add_i32 m0, s51, 0x6000
	s_nop 0
	global_load_lds_dwordx4 v150, s[48:49]
	s_waitcnt vmcnt(8)
	s_waitcnt lgkmcnt(0)
	s_barrier
	s_setprio 1
	s_waitcnt lgkmcnt(0)
	v_mfma_f32_16x16x32_bf16 v[126:129], v[130:133], v[214:217], v[126:129]
	v_mfma_f32_16x16x32_bf16 v[122:125], v[138:141], v[214:217], v[122:125]
	v_mfma_f32_16x16x32_bf16 v[114:117], v[130:133], v[222:225], v[114:117]
	v_mfma_f32_16x16x32_bf16 v[110:113], v[138:141], v[222:225], v[110:113]
	v_mfma_f32_16x16x32_bf16 v[98:101], v[130:133], v[230:233], v[98:101]
	v_mfma_f32_16x16x32_bf16 v[94:97], v[138:141], v[230:233], v[94:97]
	v_mfma_f32_16x16x32_bf16 v[82:85], v[130:133], v[238:241], v[82:85]
	v_mfma_f32_16x16x32_bf16 v[78:81], v[138:141], v[238:241], v[78:81]
	v_mfma_f32_16x16x32_bf16 v[126:129], v[134:137], v[218:221], v[126:129]
	v_mfma_f32_16x16x32_bf16 v[122:125], v[142:145], v[218:221], v[122:125]
	v_mfma_f32_16x16x32_bf16 v[114:117], v[134:137], v[226:229], v[114:117]
	v_mfma_f32_16x16x32_bf16 v[110:113], v[142:145], v[226:229], v[110:113]
	v_mfma_f32_16x16x32_bf16 v[98:101], v[134:137], v[234:237], v[98:101]
	v_mfma_f32_16x16x32_bf16 v[94:97], v[142:145], v[234:237], v[94:97]
	v_mfma_f32_16x16x32_bf16 v[82:85], v[134:137], v[242:245], v[82:85]
	v_mfma_f32_16x16x32_bf16 v[78:81], v[142:145], v[242:245], v[78:81]
	s_setprio 0
	s_setprio 1
	v_mfma_f32_16x16x32_bf16 v[118:121], v[198:201], v[214:217], v[118:121]
	v_mfma_f32_16x16x32_bf16 v[106:109], v[206:209], v[214:217], v[106:109]
	v_mfma_f32_16x16x32_bf16 v[102:105], v[198:201], v[222:225], v[102:105]
	v_mfma_f32_16x16x32_bf16 v[90:93], v[206:209], v[222:225], v[90:93]
	v_mfma_f32_16x16x32_bf16 v[86:89], v[198:201], v[230:233], v[86:89]
	v_mfma_f32_16x16x32_bf16 v[74:77], v[206:209], v[230:233], v[74:77]
	v_mfma_f32_16x16x32_bf16 v[70:73], v[198:201], v[238:241], v[70:73]
	v_mfma_f32_16x16x32_bf16 v[66:69], v[206:209], v[238:241], v[66:69]
	v_mfma_f32_16x16x32_bf16 v[118:121], v[202:205], v[218:221], v[118:121]
	v_mfma_f32_16x16x32_bf16 v[106:109], v[210:213], v[218:221], v[106:109]
	v_mfma_f32_16x16x32_bf16 v[102:105], v[202:205], v[226:229], v[102:105]
	v_mfma_f32_16x16x32_bf16 v[90:93], v[210:213], v[226:229], v[90:93]
	v_mfma_f32_16x16x32_bf16 v[86:89], v[202:205], v[234:237], v[86:89]
	v_mfma_f32_16x16x32_bf16 v[74:77], v[210:213], v[234:237], v[74:77]
	v_mfma_f32_16x16x32_bf16 v[70:73], v[202:205], v[242:245], v[70:73]
	v_mfma_f32_16x16x32_bf16 v[66:69], v[210:213], v[242:245], v[66:69]
	s_setprio 0
	s_barrier
	s_add_i32 s2, s2, s3
	s_add_i32 m0, s2, 0xffffff80
	ds_read_b128 v[214:217], v196 offset:49152
	ds_read_b128 v[218:221], v196 offset:50176
	ds_read_b128 v[222:225], v196 offset:51200
	ds_read_b128 v[226:229], v196 offset:52224
	ds_read_b128 v[230:233], v196 offset:53248
	ds_read_b128 v[234:237], v196 offset:54272
	ds_read_b128 v[238:241], v196 offset:55296
	ds_read_b128 v[242:245], v196 offset:56320
	global_load_lds_dwordx4 v148, s[58:59] offset:128
	s_add_i32 m0, s2, 0x1f80
	s_add_u32 s48, s58, 0x40080
	s_addc_u32 s49, s59, 0
	s_add_i32 s2, s41, s3
	global_load_lds_dwordx4 v150, s[58:59] offset:128
	s_mov_b32 m0, s2
	s_nop 0
	global_load_lds_dwordx4 v148, s[48:49]
	s_add_i32 m0, s2, 0x2000
	s_nop 0
	global_load_lds_dwordx4 v150, s[48:49]
	s_add_i32 m0, s51, 0x7f80
	s_nop 0
	global_load_lds_dwordx4 v148, s[60:61] offset:128
	s_add_i32 m0, s51, 0x9f80
	s_nop 0
	global_load_lds_dwordx4 v150, s[60:61] offset:128
	s_waitcnt vmcnt(8)
	s_waitcnt lgkmcnt(0)
	s_barrier
	s_setprio 1
	s_waitcnt lgkmcnt(0)
	v_mfma_f32_16x16x32_bf16 v[62:65], v[130:133], v[214:217], v[62:65]
	v_mfma_f32_16x16x32_bf16 v[58:61], v[138:141], v[214:217], v[58:61]
	v_mfma_f32_16x16x32_bf16 v[50:53], v[130:133], v[222:225], v[50:53]
	v_mfma_f32_16x16x32_bf16 v[42:45], v[138:141], v[222:225], v[42:45]
	v_mfma_f32_16x16x32_bf16 v[22:25], v[130:133], v[230:233], v[22:25]
	v_mfma_f32_16x16x32_bf16 v[18:21], v[138:141], v[230:233], v[18:21]
	v_mfma_f32_16x16x32_bf16 v[6:9], v[130:133], v[238:241], v[6:9]
	v_mfma_f32_16x16x32_bf16 v[2:5], v[138:141], v[238:241], v[2:5]
	v_mfma_f32_16x16x32_bf16 v[62:65], v[134:137], v[218:221], v[62:65]
	v_mfma_f32_16x16x32_bf16 v[58:61], v[142:145], v[218:221], v[58:61]
	v_mfma_f32_16x16x32_bf16 v[50:53], v[134:137], v[226:229], v[50:53]
	v_mfma_f32_16x16x32_bf16 v[42:45], v[142:145], v[226:229], v[42:45]
	v_mfma_f32_16x16x32_bf16 v[22:25], v[134:137], v[234:237], v[22:25]
	v_mfma_f32_16x16x32_bf16 v[18:21], v[142:145], v[234:237], v[18:21]
	v_mfma_f32_16x16x32_bf16 v[6:9], v[134:137], v[242:245], v[6:9]
	v_mfma_f32_16x16x32_bf16 v[2:5], v[142:145], v[242:245], v[2:5]
	s_setprio 0
	s_setprio 1
	v_mfma_f32_16x16x32_bf16 v[54:57], v[198:201], v[214:217], v[54:57]
	v_mfma_f32_16x16x32_bf16 v[38:41], v[206:209], v[214:217], v[38:41]
	v_mfma_f32_16x16x32_bf16 v[30:33], v[198:201], v[222:225], v[30:33]
	v_mfma_f32_16x16x32_bf16 v[10:13], v[206:209], v[222:225], v[10:13]
	v_mfma_f32_16x16x32_bf16 v[46:49], v[198:201], v[230:233], v[46:49]
	v_mfma_f32_16x16x32_bf16 v[34:37], v[206:209], v[230:233], v[34:37]
	v_mfma_f32_16x16x32_bf16 v[26:29], v[198:201], v[238:241], v[26:29]
	v_mfma_f32_16x16x32_bf16 v[14:17], v[206:209], v[238:241], v[14:17]
	v_mfma_f32_16x16x32_bf16 v[54:57], v[202:205], v[218:221], v[54:57]
	v_mfma_f32_16x16x32_bf16 v[38:41], v[210:213], v[218:221], v[38:41]
	v_mfma_f32_16x16x32_bf16 v[30:33], v[202:205], v[226:229], v[30:33]
	v_mfma_f32_16x16x32_bf16 v[10:13], v[210:213], v[226:229], v[10:13]
	v_mfma_f32_16x16x32_bf16 v[46:49], v[202:205], v[234:237], v[46:49]
	v_mfma_f32_16x16x32_bf16 v[34:37], v[210:213], v[234:237], v[34:37]
	v_mfma_f32_16x16x32_bf16 v[26:29], v[202:205], v[242:245], v[26:29]
	v_mfma_f32_16x16x32_bf16 v[14:17], v[210:213], v[242:245], v[14:17]
	s_setprio 0
	s_barrier
	s_add_i32 s39, s39, 2
	s_add_u32 s29, s29, 0x100
	s_addc_u32 s31, s31, 0
	s_cmp_gt_u32 s39, 13
	s_mov_b64 s[48:49], s[56:57]
	s_cbranch_scc0 .LBB0_879
	s_and_b64 vcc, exec, s[18:19]
	s_cbranch_vccz .LBB0_882
	s_barrier

; #define STAGE(bufoff, gbase) do { _Pragma("unroll") for (int _i = 0; _i < 2; ++_i) \
;     __builtin_amdgcn_global_load_lds((const unsigned*)((const char*)(gbase) + voff[_i]), (__attribute__((address_space(3))) unsigned*)(lds + (bufoff) + ldsw + _i * 8192), 16, 0, 0); } while (0)
; #define LDA(dst, b, h) do { _Pragma("unroll") for (int m = 0; m < 4; ++m) _Pragma("unroll") for (int k = 0; k < 2; ++k) dst[m][k] = *(const __attribute__((address_space(3))) bf16x8*)(lds + SA(b, h) + aoff + m * 2048 + k * 1024); } while (0)
; #define LDB(dst, b, h) do { _Pragma("unroll") for (int n = 0; n < 2; ++n) _Pragma("unroll") for (int k = 0; k < 2; ++k) dst[n][k] = *(const __attribute__((address_space(3))) bf16x8*)(lds + SB(b, h) + boff + n * 2048 + k * 1024); } while (0)
; #define MMA(ai, bj, At_, Bt_) do { __builtin_amdgcn_s_setprio(1); \
;     _Pragma("unroll") for (int m = 0; m < 4; ++m) _Pragma("unroll") for (int n = 0; n < 2; ++n) _Pragma("unroll") for (int k = 0; k < 2; ++k) \
;       acc[ai][bj][m][n] = MFMA16(Bt_[n][k], At_[m][k], acc[ai][bj][m][n]); \
;     __builtin_amdgcn_s_setprio(0); } while (0)
; #define WAIT_V(n) asm volatile("s_waitcnt vmcnt(" #n ")" ::: "memory")
; #define WAIT_L(n) asm volatile("s_waitcnt lgkmcnt(" #n ")" ::: "memory")
; #define BAR __builtin_amdgcn_s_barrier()
; #define SCHED __builtin_amdgcn_sched_barrier(0)
; DI void gemm_phase(const GemmArgs& g, char* shm_c) {
;     ...
;     for (int t = 0; t < nt; t += 2) {
;       const bool last = t == nt - 2;
;       const char* a1 = cA + (size_t)(t + 1) * kstep;
;       const char* a2 = last ? nA : cA + (size_t)(t + 2) * kstep; const char* b2 = last ? nB : cB + (size_t)(t + 2) * kstep;
;       const char* a3 = a2 + kstep; const char* b3 = b2 + kstep;
;       LDB(B0, 0, 0); LDB(B1, 0, 1); SCHED; LDA(At, 0, 0); STAGE(SA(1, 1), a1 + hstep);
;       WAIT_V(8); WAIT_L(0); BAR; MMA(0, 0, At, B0); MMA(0, 1, At, B1); BAR; SCHED;
;       LDA(At, 0, 1); STAGE(SB(0, 0), b2); STAGE(SB(0, 1), b2 + hstep); STAGE(SA(0, 0), a2);
;       WAIT_V(8); WAIT_L(0); BAR; MMA(1, 0, At, B0); MMA(1, 1, At, B1); BAR; SCHED;
.LBB0_1040:
	s_add_u32 s34, s30, 0x100
	s_addc_u32 s35, s31, 0
	s_add_i32 s2, 0, 0x10000
	s_cmp_eq_u32 s3, 12
	s_cselect_b32 s39, s23, s35
	s_cselect_b32 s38, s22, s34
	v_add_u32_e32 v138, s2, v141
	s_cselect_b32 s37, s25, s1
	s_cselect_b32 s36, s24, s0
	s_add_i32 s21, 0, 0x14000
	ds_read_b128 v[144:147], v138
	ds_read_b128 v[148:151], v138 offset:1024
	ds_read_b128 v[152:155], v138 offset:2048
	ds_read_b128 v[192:195], v138 offset:3072
	v_add_u32_e32 v138, s21, v141
	ds_read_b128 v[196:199], v138
	ds_read_b128 v[200:203], v138 offset:1024
	ds_read_b128 v[204:207], v138 offset:2048
	ds_read_b128 v[208:211], v138 offset:3072
	s_add_i32 s19, s60, 0
	s_add_i32 m0, s19, 0xc000
	ds_read_b128 v[212:215], v142
	ds_read_b128 v[216:219], v142 offset:1024
	ds_read_b128 v[220:223], v142 offset:2048
	ds_read_b128 v[224:227], v142 offset:3072
	ds_read_b128 v[228:231], v142 offset:4096
	ds_read_b128 v[232:235], v142 offset:5120
	ds_read_b128 v[236:239], v142 offset:6144
	ds_read_b128 v[240:243], v142 offset:7168
	global_load_lds_dwordx4 v134, s[30:31]
	s_add_i32 m0, s19, 0xe000
	s_nop 0
	global_load_lds_dwordx4 v136, s[30:31]
	s_waitcnt vmcnt(8)
	s_waitcnt lgkmcnt(0)
	s_barrier
	s_setprio 1
	s_waitcnt lgkmcnt(0)
	v_mfma_f32_16x16x32_bf16 v[126:129], v[144:147], v[212:215], v[126:129]
	v_mfma_f32_16x16x32_bf16 v[122:125], v[152:155], v[212:215], v[122:125]
	v_mfma_f32_16x16x32_bf16 v[110:113], v[144:147], v[220:223], v[110:113]
	v_mfma_f32_16x16x32_bf16 v[106:109], v[152:155], v[220:223], v[106:109]
	v_mfma_f32_16x16x32_bf16 v[94:97], v[144:147], v[228:231], v[94:97]
	v_mfma_f32_16x16x32_bf16 v[90:93], v[152:155], v[228:231], v[90:93]
	v_mfma_f32_16x16x32_bf16 v[78:81], v[144:147], v[236:239], v[78:81]
	v_mfma_f32_16x16x32_bf16 v[74:77], v[152:155], v[236:239], v[74:77]
	v_mfma_f32_16x16x32_bf16 v[126:129], v[148:151], v[216:219], v[126:129]
	v_mfma_f32_16x16x32_bf16 v[122:125], v[192:195], v[216:219], v[122:125]
	v_mfma_f32_16x16x32_bf16 v[110:113], v[148:151], v[224:227], v[110:113]
	v_mfma_f32_16x16x32_bf16 v[106:109], v[192:195], v[224:227], v[106:109]
	v_mfma_f32_16x16x32_bf16 v[94:97], v[148:151], v[232:235], v[94:97]
	v_mfma_f32_16x16x32_bf16 v[90:93], v[192:195], v[232:235], v[90:93]
	v_mfma_f32_16x16x32_bf16 v[78:81], v[148:151], v[240:243], v[78:81]
	v_mfma_f32_16x16x32_bf16 v[74:77], v[192:195], v[240:243], v[74:77]
	s_setprio 0
	s_setprio 1
	v_mfma_f32_16x16x32_bf16 v[118:121], v[196:199], v[212:215], v[118:121]
	v_mfma_f32_16x16x32_bf16 v[114:117], v[204:207], v[212:215], v[114:117]
	v_mfma_f32_16x16x32_bf16 v[102:105], v[196:199], v[220:223], v[102:105]
	v_mfma_f32_16x16x32_bf16 v[98:101], v[204:207], v[220:223], v[98:101]
	v_mfma_f32_16x16x32_bf16 v[86:89], v[196:199], v[228:231], v[86:89]
	v_mfma_f32_16x16x32_bf16 v[82:85], v[204:207], v[228:231], v[82:85]
	v_mfma_f32_16x16x32_bf16 v[70:73], v[196:199], v[236:239], v[70:73]
	v_mfma_f32_16x16x32_bf16 v[66:69], v[204:207], v[236:239], v[66:69]
	v_mfma_f32_16x16x32_bf16 v[118:121], v[200:203], v[216:219], v[118:121]
	v_mfma_f32_16x16x32_bf16 v[114:117], v[208:211], v[216:219], v[114:117]
	v_mfma_f32_16x16x32_bf16 v[102:105], v[200:203], v[224:227], v[102:105]
	v_mfma_f32_16x16x32_bf16 v[98:101], v[208:211], v[224:227], v[98:101]
	v_mfma_f32_16x16x32_bf16 v[86:89], v[200:203], v[232:235], v[86:89]
	v_mfma_f32_16x16x32_bf16 v[82:85], v[208:211], v[232:235], v[82:85]
	v_mfma_f32_16x16x32_bf16 v[70:73], v[200:203], v[240:243], v[70:73]
	v_mfma_f32_16x16x32_bf16 v[66:69], v[208:211], v[240:243], v[66:69]
	s_setprio 0
	s_barrier
	s_add_i32 s2, s2, s60
	s_mov_b32 m0, s2
	ds_read_b128 v[212:215], v142 offset:16384
	ds_read_b128 v[216:219], v142 offset:17408
	ds_read_b128 v[220:223], v142 offset:18432
	ds_read_b128 v[224:227], v142 offset:19456
	ds_read_b128 v[228:231], v142 offset:20480
	ds_read_b128 v[232:235], v142 offset:21504
	ds_read_b128 v[236:239], v142 offset:22528
	ds_read_b128 v[240:243], v142 offset:23552
	global_load_lds_dwordx4 v130, s[36:37]
	s_add_i32 m0, s2, 0x2000
	s_add_u32 s30, s36, 0x40000
	s_addc_u32 s31, s37, 0
	s_add_i32 s2, s21, s60
	global_load_lds_dwordx4 v132, s[36:37]
	s_mov_b32 m0, s2
	s_nop 0
	global_load_lds_dwordx4 v130, s[30:31]
	s_add_i32 m0, s2, 0x2000
	s_nop 0
	global_load_lds_dwordx4 v132, s[30:31]
	s_mov_b32 m0, s19
	s_nop 0
	global_load_lds_dwordx4 v130, s[38:39]
	s_add_i32 m0, s19, 0x2000
	s_nop 0
	global_load_lds_dwordx4 v132, s[38:39]
	s_waitcnt vmcnt(8)
	s_waitcnt lgkmcnt(0)
	s_barrier
	s_setprio 1
	s_waitcnt lgkmcnt(0)
	v_mfma_f32_16x16x32_bf16 v[62:65], v[144:147], v[212:215], v[62:65]
	v_mfma_f32_16x16x32_bf16 v[58:61], v[152:155], v[212:215], v[58:61]
	v_mfma_f32_16x16x32_bf16 v[46:49], v[144:147], v[220:223], v[46:49]
	v_mfma_f32_16x16x32_bf16 v[42:45], v[152:155], v[220:223], v[42:45]
	v_mfma_f32_16x16x32_bf16 v[30:33], v[144:147], v[228:231], v[30:33]
	v_mfma_f32_16x16x32_bf16 v[26:29], v[152:155], v[228:231], v[26:29]
	v_mfma_f32_16x16x32_bf16 v[14:17], v[144:147], v[236:239], v[14:17]
	v_mfma_f32_16x16x32_bf16 v[2:5], v[152:155], v[236:239], v[2:5]
	v_mfma_f32_16x16x32_bf16 v[62:65], v[148:151], v[216:219], v[62:65]
	v_mfma_f32_16x16x32_bf16 v[58:61], v[192:195], v[216:219], v[58:61]
	v_mfma_f32_16x16x32_bf16 v[46:49], v[148:151], v[224:227], v[46:49]
	v_mfma_f32_16x16x32_bf16 v[42:45], v[192:195], v[224:227], v[42:45]
	v_mfma_f32_16x16x32_bf16 v[30:33], v[148:151], v[232:235], v[30:33]
	v_mfma_f32_16x16x32_bf16 v[26:29], v[192:195], v[232:235], v[26:29]
	v_mfma_f32_16x16x32_bf16 v[14:17], v[148:151], v[240:243], v[14:17]
	v_mfma_f32_16x16x32_bf16 v[2:5], v[192:195], v[240:243], v[2:5]
	s_setprio 0
	s_setprio 1
	v_mfma_f32_16x16x32_bf16 v[54:57], v[196:199], v[212:215], v[54:57]
	v_mfma_f32_16x16x32_bf16 v[50:53], v[204:207], v[212:215], v[50:53]
	v_mfma_f32_16x16x32_bf16 v[38:41], v[196:199], v[220:223], v[38:41]
	v_mfma_f32_16x16x32_bf16 v[34:37], v[204:207], v[220:223], v[34:37]
	v_mfma_f32_16x16x32_bf16 v[18:21], v[196:199], v[228:231], v[18:21]
	v_mfma_f32_16x16x32_bf16 v[22:25], v[204:207], v[228:231], v[22:25]
	v_mfma_f32_16x16x32_bf16 v[6:9], v[196:199], v[236:239], v[6:9]
	v_mfma_f32_16x16x32_bf16 v[10:13], v[204:207], v[236:239], v[10:13]
	v_mfma_f32_16x16x32_bf16 v[54:57], v[200:203], v[216:219], v[54:57]
	v_mfma_f32_16x16x32_bf16 v[50:53], v[208:211], v[216:219], v[50:53]
	v_mfma_f32_16x16x32_bf16 v[38:41], v[200:203], v[224:227], v[38:41]
	v_mfma_f32_16x16x32_bf16 v[34:37], v[208:211], v[224:227], v[34:37]
	v_mfma_f32_16x16x32_bf16 v[18:21], v[200:203], v[232:235], v[18:21]
	v_mfma_f32_16x16x32_bf16 v[22:25], v[208:211], v[232:235], v[22:25]
	v_mfma_f32_16x16x32_bf16 v[6:9], v[200:203], v[240:243], v[6:9]
	v_mfma_f32_16x16x32_bf16 v[10:13], v[208:211], v[240:243], v[10:13]
	s_setprio 0
	s_barrier
; #define STAGE(bufoff, gbase) do { _Pragma("unroll") for (int _i = 0; _i < 2; ++_i) \
;     __builtin_amdgcn_global_load_lds((const unsigned*)((const char*)(gbase) + voff[_i]), (__attribute__((address_space(3))) unsigned*)(lds + (bufoff) + ldsw + _i * 8192), 16, 0, 0); } while (0)
; #define LDA(dst, b, h) do { _Pragma("unroll") for (int m = 0; m < 4; ++m) _Pragma("unroll") for (int k = 0; k < 2; ++k) dst[m][k] = *(const __attribute__((address_space(3))) bf16x8*)(lds + SA(b, h) + aoff + m * 2048 + k * 1024); } while (0)
; #define LDB(dst, b, h) do { _Pragma("unroll") for (int n = 0; n < 2; ++n) _Pragma("unroll") for (int k = 0; k < 2; ++k) dst[n][k] = *(const __attribute__((address_space(3))) bf16x8*)(lds + SB(b, h) + boff + n * 2048 + k * 1024); } while (0)
; #define MMA(ai, bj, At_, Bt_) do { __builtin_amdgcn_s_setprio(1); \
;     _Pragma("unroll") for (int m = 0; m < 4; ++m) _Pragma("unroll") for (int n = 0; n < 2; ++n) _Pragma("unroll") for (int k = 0; k < 2; ++k) \
;       acc[ai][bj][m][n] = MFMA16(Bt_[n][k], At_[m][k], acc[ai][bj][m][n]); \
;     __builtin_amdgcn_s_setprio(0); } while (0)
; #define WAIT_V(n) asm volatile("s_waitcnt vmcnt(" #n ")" ::: "memory")
; #define WAIT_L(n) asm volatile("s_waitcnt lgkmcnt(" #n ")" ::: "memory")
; #define BAR __builtin_amdgcn_s_barrier()
; #define SCHED __builtin_amdgcn_sched_barrier(0)
; DI void gemm_phase(const GemmArgs& g, char* shm_c) {
;     ...
;       LDB(B0, 1, 0); LDB(B1, 1, 1); SCHED; LDA(At, 1, 0); STAGE(SA(0, 1), a2 + hstep);
;       WAIT_V(8); WAIT_L(0); BAR; MMA(0, 0, At, B0); MMA(0, 1, At, B1); BAR; SCHED;
;       LDA(At, 1, 1); STAGE(SB(1, 0), b3); STAGE(SB(1, 1), b3 + hstep); STAGE(SA(1, 0), a3);
;       WAIT_V(8); WAIT_L(0); BAR; MMA(1, 0, At, B0); MMA(1, 1, At, B1); BAR; SCHED;
;     }
	s_add_i32 s2, 0, 0x18000
	v_add_u32_e32 v143, s2, v141
	s_add_i32 s21, 0, 0x1c000
	ds_read_b128 v[144:147], v143
	ds_read_b128 v[148:151], v143 offset:1024
	ds_read_b128 v[152:155], v143 offset:2048
	ds_read_b128 v[192:195], v143 offset:3072
	v_add_u32_e32 v143, s21, v141
	ds_read_b128 v[196:199], v143
	ds_read_b128 v[200:203], v143 offset:1024
	ds_read_b128 v[204:207], v143 offset:2048
	ds_read_b128 v[208:211], v143 offset:3072
	s_add_u32 s30, s38, 0x40000
	s_addc_u32 s31, s39, 0
	s_add_i32 m0, s19, 0x4000
	ds_read_b128 v[212:215], v142 offset:32768
	ds_read_b128 v[216:219], v142 offset:33792
	ds_read_b128 v[220:223], v142 offset:34816
	ds_read_b128 v[224:227], v142 offset:35840
	ds_read_b128 v[228:231], v142 offset:36864
	ds_read_b128 v[232:235], v142 offset:37888
	ds_read_b128 v[236:239], v142 offset:38912
	ds_read_b128 v[240:243], v142 offset:39936
	global_load_lds_dwordx4 v130, s[30:31]
	s_add_i32 m0, s19, 0x6000
	s_nop 0
	global_load_lds_dwordx4 v132, s[30:31]
	s_waitcnt vmcnt(8)
	s_waitcnt lgkmcnt(0)
	s_barrier
	s_setprio 1
	s_waitcnt lgkmcnt(0)
	v_mfma_f32_16x16x32_bf16 v[126:129], v[144:147], v[212:215], v[126:129]
	v_mfma_f32_16x16x32_bf16 v[122:125], v[152:155], v[212:215], v[122:125]
	v_mfma_f32_16x16x32_bf16 v[110:113], v[144:147], v[220:223], v[110:113]
	v_mfma_f32_16x16x32_bf16 v[106:109], v[152:155], v[220:223], v[106:109]
	v_mfma_f32_16x16x32_bf16 v[94:97], v[144:147], v[228:231], v[94:97]
	v_mfma_f32_16x16x32_bf16 v[90:93], v[152:155], v[228:231], v[90:93]
	v_mfma_f32_16x16x32_bf16 v[78:81], v[144:147], v[236:239], v[78:81]
	v_mfma_f32_16x16x32_bf16 v[74:77], v[152:155], v[236:239], v[74:77]
	v_mfma_f32_16x16x32_bf16 v[126:129], v[148:151], v[216:219], v[126:129]
	v_mfma_f32_16x16x32_bf16 v[122:125], v[192:195], v[216:219], v[122:125]
	v_mfma_f32_16x16x32_bf16 v[110:113], v[148:151], v[224:227], v[110:113]
	v_mfma_f32_16x16x32_bf16 v[106:109], v[192:195], v[224:227], v[106:109]
	v_mfma_f32_16x16x32_bf16 v[94:97], v[148:151], v[232:235], v[94:97]
	v_mfma_f32_16x16x32_bf16 v[90:93], v[192:195], v[232:235], v[90:93]
	v_mfma_f32_16x16x32_bf16 v[78:81], v[148:151], v[240:243], v[78:81]
	v_mfma_f32_16x16x32_bf16 v[74:77], v[192:195], v[240:243], v[74:77]
	s_setprio 0
	s_setprio 1
	v_mfma_f32_16x16x32_bf16 v[118:121], v[196:199], v[212:215], v[118:121]
	v_mfma_f32_16x16x32_bf16 v[114:117], v[204:207], v[212:215], v[114:117]
	v_mfma_f32_16x16x32_bf16 v[102:105], v[196:199], v[220:223], v[102:105]
	v_mfma_f32_16x16x32_bf16 v[98:101], v[204:207], v[220:223], v[98:101]
	v_mfma_f32_16x16x32_bf16 v[86:89], v[196:199], v[228:231], v[86:89]
	v_mfma_f32_16x16x32_bf16 v[82:85], v[204:207], v[228:231], v[82:85]
	v_mfma_f32_16x16x32_bf16 v[70:73], v[196:199], v[236:239], v[70:73]
	v_mfma_f32_16x16x32_bf16 v[66:69], v[204:207], v[236:239], v[66:69]
	v_mfma_f32_16x16x32_bf16 v[118:121], v[200:203], v[216:219], v[118:121]
	v_mfma_f32_16x16x32_bf16 v[114:117], v[208:211], v[216:219], v[114:117]
	v_mfma_f32_16x16x32_bf16 v[102:105], v[200:203], v[224:227], v[102:105]
	v_mfma_f32_16x16x32_bf16 v[98:101], v[208:211], v[224:227], v[98:101]
	v_mfma_f32_16x16x32_bf16 v[86:89], v[200:203], v[232:235], v[86:89]
	v_mfma_f32_16x16x32_bf16 v[82:85], v[208:211], v[232:235], v[82:85]
	v_mfma_f32_16x16x32_bf16 v[70:73], v[200:203], v[240:243], v[70:73]
	v_mfma_f32_16x16x32_bf16 v[66:69], v[208:211], v[240:243], v[66:69]
	s_setprio 0
	s_barrier
	s_add_i32 s2, s2, s60
	s_add_i32 m0, s2, 0xffffff80
	ds_read_b128 v[212:215], v142 offset:49152
	ds_read_b128 v[216:219], v142 offset:50176
	ds_read_b128 v[220:223], v142 offset:51200
	ds_read_b128 v[224:227], v142 offset:52224
	ds_read_b128 v[228:231], v142 offset:53248
	ds_read_b128 v[232:235], v142 offset:54272
	ds_read_b128 v[236:239], v142 offset:55296
	ds_read_b128 v[240:243], v142 offset:56320
	global_load_lds_dwordx4 v130, s[36:37] offset:128
	s_add_i32 m0, s2, 0x1f80
	s_add_u32 s30, s36, 0x40080
	s_addc_u32 s31, s37, 0
	s_add_i32 s2, s21, s60
	global_load_lds_dwordx4 v132, s[36:37] offset:128
	s_mov_b32 m0, s2
	s_nop 0
	global_load_lds_dwordx4 v130, s[30:31]
	s_add_i32 m0, s2, 0x2000
	s_nop 0
	global_load_lds_dwordx4 v132, s[30:31]
	s_add_i32 m0, s19, 0x7f80
	s_nop 0
	global_load_lds_dwordx4 v130, s[38:39] offset:128
	s_add_i32 m0, s19, 0x9f80
	s_nop 0
	global_load_lds_dwordx4 v132, s[38:39] offset:128
	s_waitcnt vmcnt(8)
	s_waitcnt lgkmcnt(0)
	s_barrier
	s_setprio 1
	s_waitcnt lgkmcnt(0)
	v_mfma_f32_16x16x32_bf16 v[62:65], v[144:147], v[212:215], v[62:65]
	v_mfma_f32_16x16x32_bf16 v[58:61], v[152:155], v[212:215], v[58:61]
	v_mfma_f32_16x16x32_bf16 v[46:49], v[144:147], v[220:223], v[46:49]
	v_mfma_f32_16x16x32_bf16 v[42:45], v[152:155], v[220:223], v[42:45]
	v_mfma_f32_16x16x32_bf16 v[30:33], v[144:147], v[228:231], v[30:33]
	v_mfma_f32_16x16x32_bf16 v[26:29], v[152:155], v[228:231], v[26:29]
	v_mfma_f32_16x16x32_bf16 v[14:17], v[144:147], v[236:239], v[14:17]
	v_mfma_f32_16x16x32_bf16 v[2:5], v[152:155], v[236:239], v[2:5]
	v_mfma_f32_16x16x32_bf16 v[62:65], v[148:151], v[216:219], v[62:65]
	v_mfma_f32_16x16x32_bf16 v[58:61], v[192:195], v[216:219], v[58:61]
	v_mfma_f32_16x16x32_bf16 v[46:49], v[148:151], v[224:227], v[46:49]
	v_mfma_f32_16x16x32_bf16 v[42:45], v[192:195], v[224:227], v[42:45]
	v_mfma_f32_16x16x32_bf16 v[30:33], v[148:151], v[232:235], v[30:33]
	v_mfma_f32_16x16x32_bf16 v[26:29], v[192:195], v[232:235], v[26:29]
	v_mfma_f32_16x16x32_bf16 v[14:17], v[148:151], v[240:243], v[14:17]
	v_mfma_f32_16x16x32_bf16 v[2:5], v[192:195], v[240:243], v[2:5]
	s_setprio 0
	s_setprio 1
	v_mfma_f32_16x16x32_bf16 v[54:57], v[196:199], v[212:215], v[54:57]
	v_mfma_f32_16x16x32_bf16 v[50:53], v[204:207], v[212:215], v[50:53]
	v_mfma_f32_16x16x32_bf16 v[38:41], v[196:199], v[220:223], v[38:41]
	v_mfma_f32_16x16x32_bf16 v[34:37], v[204:207], v[220:223], v[34:37]
	v_mfma_f32_16x16x32_bf16 v[18:21], v[196:199], v[228:231], v[18:21]
	v_mfma_f32_16x16x32_bf16 v[22:25], v[204:207], v[228:231], v[22:25]
	v_mfma_f32_16x16x32_bf16 v[6:9], v[196:199], v[236:239], v[6:9]
	v_mfma_f32_16x16x32_bf16 v[10:13], v[204:207], v[236:239], v[10:13]
	v_mfma_f32_16x16x32_bf16 v[54:57], v[200:203], v[216:219], v[54:57]
	v_mfma_f32_16x16x32_bf16 v[50:53], v[208:211], v[216:219], v[50:53]
	v_mfma_f32_16x16x32_bf16 v[38:41], v[200:203], v[224:227], v[38:41]
	v_mfma_f32_16x16x32_bf16 v[34:37], v[208:211], v[224:227], v[34:37]
	v_mfma_f32_16x16x32_bf16 v[18:21], v[200:203], v[232:235], v[18:21]
	v_mfma_f32_16x16x32_bf16 v[22:25], v[208:211], v[232:235], v[22:25]
	v_mfma_f32_16x16x32_bf16 v[6:9], v[200:203], v[240:243], v[6:9]
	v_mfma_f32_16x16x32_bf16 v[10:13], v[208:211], v[240:243], v[10:13]
	s_setprio 0
	s_barrier
	s_add_i32 s3, s3, 2
	s_add_u32 s0, s0, 0x100
	s_addc_u32 s1, s1, 0
	s_cmp_gt_u32 s3, 13
	s_mov_b64 s[30:31], s[34:35]
	s_cbranch_scc0 .LBB0_1040
	s_and_b64 vcc, exec, s[6:7]
	s_cbranch_vccz .LBB0_1043
	s_barrier

; #define STAGE(bufoff, gbase) do { _Pragma("unroll") for (int _i = 0; _i < 2; ++_i) \
;     __builtin_amdgcn_global_load_lds((const unsigned*)((const char*)(gbase) + voff[_i]), (__attribute__((address_space(3))) unsigned*)(lds + (bufoff) + ldsw + _i * 8192), 16, 0, 0); } while (0)
; #define LDA(dst, b, h) do { _Pragma("unroll") for (int m = 0; m < 4; ++m) _Pragma("unroll") for (int k = 0; k < 2; ++k) dst[m][k] = *(const __attribute__((address_space(3))) bf16x8*)(lds + SA(b, h) + aoff + m * 2048 + k * 1024); } while (0)
; #define LDB(dst, b, h) do { _Pragma("unroll") for (int n = 0; n < 2; ++n) _Pragma("unroll") for (int k = 0; k < 2; ++k) dst[n][k] = *(const __attribute__((address_space(3))) bf16x8*)(lds + SB(b, h) + boff + n * 2048 + k * 1024); } while (0)
; #define MMA(ai, bj, At_, Bt_) do { __builtin_amdgcn_s_setprio(1); \
;     _Pragma("unroll") for (int m = 0; m < 4; ++m) _Pragma("unroll") for (int n = 0; n < 2; ++n) _Pragma("unroll") for (int k = 0; k < 2; ++k) \
;       acc[ai][bj][m][n] = MFMA16(Bt_[n][k], At_[m][k], acc[ai][bj][m][n]); \
;     __builtin_amdgcn_s_setprio(0); } while (0)
; #define WAIT_V(n) asm volatile("s_waitcnt vmcnt(" #n ")" ::: "memory")
; #define WAIT_L(n) asm volatile("s_waitcnt lgkmcnt(" #n ")" ::: "memory")
; #define BAR __builtin_amdgcn_s_barrier()
; #define SCHED __builtin_amdgcn_sched_barrier(0)
; DI void gemm_phase(const GemmArgs& g, char* shm_c) {
;     ...
;     for (int t = 0; t < nt; t += 2) {
;       const bool last = t == nt - 2;
;       const char* a1 = cA + (size_t)(t + 1) * kstep;
;       const char* a2 = last ? nA : cA + (size_t)(t + 2) * kstep; const char* b2 = last ? nB : cB + (size_t)(t + 2) * kstep;
;       const char* a3 = a2 + kstep; const char* b3 = b2 + kstep;
;       LDB(B0, 0, 0); LDB(B1, 0, 1); SCHED; LDA(At, 0, 0); STAGE(SA(1, 1), a1 + hstep);
;       WAIT_V(8); WAIT_L(0); BAR; MMA(0, 0, At, B0); MMA(0, 1, At, B1); BAR; SCHED;
;       LDA(At, 0, 1); STAGE(SB(0, 0), b2); STAGE(SB(0, 1), b2 + hstep); STAGE(SA(0, 0), a2);
;       WAIT_V(8); WAIT_L(0); BAR; MMA(1, 0, At, B0); MMA(1, 1, At, B1); BAR; SCHED;
.LBB0_1119:
	s_add_u32 s26, s24, 0x100
	s_addc_u32 s27, s25, 0
	s_add_i32 s2, 0, 0x10000
	s_cmp_eq_u32 s48, 40
	s_cselect_b32 s31, s21, s27
	s_cselect_b32 s30, s20, s26
	s_cselect_b32 s29, s23, s33
	s_cselect_b32 s28, s22, s3
	s_add_i32 s41, 0, 0x14000
	v_add_u32_e32 v102, s2, v195
	v_add_u32_e32 v154, s41, v195
	ds_read_b128 v[50:53], v102
	ds_read_b128 v[86:89], v102 offset:1024
	ds_read_b128 v[90:93], v102 offset:2048
	ds_read_b128 v[102:105], v102 offset:3072
	ds_read_b128 v[198:201], v154
	ds_read_b128 v[202:205], v154 offset:1024
	ds_read_b128 v[206:209], v154 offset:2048
	ds_read_b128 v[210:213], v154 offset:3072
	s_add_i32 s49, s36, 0
	s_add_i32 m0, s49, 0xc000
	ds_read_b128 v[214:217], v196
	ds_read_b128 v[218:221], v196 offset:1024
	ds_read_b128 v[222:225], v196 offset:2048
	ds_read_b128 v[226:229], v196 offset:3072
	ds_read_b128 v[230:233], v196 offset:4096
	ds_read_b128 v[234:237], v196 offset:5120
	ds_read_b128 v[238:241], v196 offset:6144
	ds_read_b128 v[242:245], v196 offset:7168
	global_load_lds_dwordx4 v150, s[24:25]
	s_add_i32 m0, s49, 0xe000
	s_nop 0
	global_load_lds_dwordx4 v152, s[24:25]
	s_waitcnt vmcnt(8)
	s_waitcnt lgkmcnt(0)
	s_barrier
	s_setprio 1
	s_waitcnt lgkmcnt(0)
	v_mfma_f32_16x16x32_bf16 v[142:145], v[50:53], v[214:217], v[142:145]
	v_mfma_f32_16x16x32_bf16 v[138:141], v[90:93], v[214:217], v[138:141]
	v_mfma_f32_16x16x32_bf16 v[126:129], v[50:53], v[222:225], v[126:129]
	v_mfma_f32_16x16x32_bf16 v[122:125], v[90:93], v[222:225], v[122:125]
	v_mfma_f32_16x16x32_bf16 v[110:113], v[50:53], v[230:233], v[110:113]
	v_mfma_f32_16x16x32_bf16 v[106:109], v[90:93], v[230:233], v[106:109]
	v_mfma_f32_16x16x32_bf16 v[82:85], v[50:53], v[238:241], v[82:85]
	v_mfma_f32_16x16x32_bf16 v[78:81], v[90:93], v[238:241], v[78:81]
	v_mfma_f32_16x16x32_bf16 v[142:145], v[86:89], v[218:221], v[142:145]
	v_mfma_f32_16x16x32_bf16 v[138:141], v[102:105], v[218:221], v[138:141]
	v_mfma_f32_16x16x32_bf16 v[126:129], v[86:89], v[226:229], v[126:129]
	v_mfma_f32_16x16x32_bf16 v[122:125], v[102:105], v[226:229], v[122:125]
	v_mfma_f32_16x16x32_bf16 v[110:113], v[86:89], v[234:237], v[110:113]
	v_mfma_f32_16x16x32_bf16 v[106:109], v[102:105], v[234:237], v[106:109]
	v_mfma_f32_16x16x32_bf16 v[82:85], v[86:89], v[242:245], v[82:85]
	v_mfma_f32_16x16x32_bf16 v[78:81], v[102:105], v[242:245], v[78:81]
	s_setprio 0
	s_setprio 1
	v_mfma_f32_16x16x32_bf16 v[134:137], v[198:201], v[214:217], v[134:137]
	v_mfma_f32_16x16x32_bf16 v[130:133], v[206:209], v[214:217], v[130:133]
	v_mfma_f32_16x16x32_bf16 v[118:121], v[198:201], v[222:225], v[118:121]
	v_mfma_f32_16x16x32_bf16 v[114:117], v[206:209], v[222:225], v[114:117]
	v_mfma_f32_16x16x32_bf16 v[98:101], v[198:201], v[230:233], v[98:101]
	v_mfma_f32_16x16x32_bf16 v[94:97], v[206:209], v[230:233], v[94:97]
	v_mfma_f32_16x16x32_bf16 v[74:77], v[198:201], v[238:241], v[74:77]
	v_mfma_f32_16x16x32_bf16 v[70:73], v[206:209], v[238:241], v[70:73]
	v_mfma_f32_16x16x32_bf16 v[134:137], v[202:205], v[218:221], v[134:137]
	v_mfma_f32_16x16x32_bf16 v[130:133], v[210:213], v[218:221], v[130:133]
	v_mfma_f32_16x16x32_bf16 v[118:121], v[202:205], v[226:229], v[118:121]
	v_mfma_f32_16x16x32_bf16 v[114:117], v[210:213], v[226:229], v[114:117]
	v_mfma_f32_16x16x32_bf16 v[98:101], v[202:205], v[234:237], v[98:101]
	v_mfma_f32_16x16x32_bf16 v[94:97], v[210:213], v[234:237], v[94:97]
	v_mfma_f32_16x16x32_bf16 v[74:77], v[202:205], v[242:245], v[74:77]
	v_mfma_f32_16x16x32_bf16 v[70:73], v[210:213], v[242:245], v[70:73]
	s_setprio 0
	s_barrier
	s_add_i32 s2, s2, s36
	s_mov_b32 m0, s2
	ds_read_b128 v[214:217], v196 offset:16384
	ds_read_b128 v[218:221], v196 offset:17408
	ds_read_b128 v[222:225], v196 offset:18432
	ds_read_b128 v[226:229], v196 offset:19456
	ds_read_b128 v[230:233], v196 offset:20480
	ds_read_b128 v[234:237], v196 offset:21504
	ds_read_b128 v[238:241], v196 offset:22528
	ds_read_b128 v[242:245], v196 offset:23552
	global_load_lds_dwordx4 v146, s[28:29]
	s_add_i32 m0, s2, 0x2000
	s_add_u32 s24, s28, 0xb0000
	s_addc_u32 s25, s29, 0
	s_add_i32 s2, s41, s36
	global_load_lds_dwordx4 v148, s[28:29]
	s_mov_b32 m0, s2
	s_nop 0
	global_load_lds_dwordx4 v146, s[24:25]
	s_add_i32 m0, s2, 0x2000
	s_nop 0
	global_load_lds_dwordx4 v148, s[24:25]
	s_mov_b32 m0, s49
	s_nop 0
	global_load_lds_dwordx4 v146, s[30:31]
	s_add_i32 m0, s49, 0x2000
	s_nop 0
	global_load_lds_dwordx4 v148, s[30:31]
	s_waitcnt vmcnt(8)
	s_waitcnt lgkmcnt(0)
	s_barrier
	s_setprio 1
	s_waitcnt lgkmcnt(0)
	v_mfma_f32_16x16x32_bf16 v[66:69], v[50:53], v[214:217], v[66:69]
	v_mfma_f32_16x16x32_bf16 v[62:65], v[90:93], v[214:217], v[62:65]
	v_mfma_f32_16x16x32_bf16 v[46:49], v[50:53], v[222:225], v[46:49]
	v_mfma_f32_16x16x32_bf16 v[42:45], v[90:93], v[222:225], v[42:45]
	v_mfma_f32_16x16x32_bf16 v[26:29], v[50:53], v[230:233], v[26:29]
	v_mfma_f32_16x16x32_bf16 v[18:21], v[90:93], v[230:233], v[18:21]
	v_mfma_f32_16x16x32_bf16 v[10:13], v[50:53], v[238:241], v[10:13]
	v_mfma_f32_16x16x32_bf16 v[6:9], v[90:93], v[238:241], v[6:9]
	v_mfma_f32_16x16x32_bf16 v[66:69], v[86:89], v[218:221], v[66:69]
	v_mfma_f32_16x16x32_bf16 v[62:65], v[102:105], v[218:221], v[62:65]
	v_mfma_f32_16x16x32_bf16 v[46:49], v[86:89], v[226:229], v[46:49]
	v_mfma_f32_16x16x32_bf16 v[42:45], v[102:105], v[226:229], v[42:45]
	v_mfma_f32_16x16x32_bf16 v[26:29], v[86:89], v[234:237], v[26:29]
	v_mfma_f32_16x16x32_bf16 v[18:21], v[102:105], v[234:237], v[18:21]
	v_mfma_f32_16x16x32_bf16 v[10:13], v[86:89], v[242:245], v[10:13]
	v_mfma_f32_16x16x32_bf16 v[6:9], v[102:105], v[242:245], v[6:9]
	s_setprio 0
	s_setprio 1
	v_mfma_f32_16x16x32_bf16 v[54:57], v[206:209], v[214:217], v[54:57]
	v_mfma_f32_16x16x32_bf16 v[38:41], v[198:201], v[222:225], v[38:41]
	v_mfma_f32_16x16x32_bf16 v[22:25], v[206:209], v[222:225], v[22:25]
	v_mfma_f32_16x16x32_bf16 v[34:37], v[198:201], v[230:233], v[34:37]
	v_mfma_f32_16x16x32_bf16 v[30:33], v[206:209], v[230:233], v[30:33]
	v_mfma_f32_16x16x32_bf16 v[14:17], v[198:201], v[238:241], v[14:17]
	v_mfma_f32_16x16x32_bf16 v[2:5], v[206:209], v[238:241], v[2:5]
	v_mfma_f32_16x16x32_bf16 v[50:53], v[198:201], v[214:217], v[58:61]
	v_mfma_f32_16x16x32_bf16 v[54:57], v[210:213], v[218:221], v[54:57]
	v_mfma_f32_16x16x32_bf16 v[38:41], v[202:205], v[226:229], v[38:41]
	v_mfma_f32_16x16x32_bf16 v[22:25], v[210:213], v[226:229], v[22:25]
	v_mfma_f32_16x16x32_bf16 v[34:37], v[202:205], v[234:237], v[34:37]
	v_mfma_f32_16x16x32_bf16 v[30:33], v[210:213], v[234:237], v[30:33]
	v_mfma_f32_16x16x32_bf16 v[14:17], v[202:205], v[242:245], v[14:17]
	v_mfma_f32_16x16x32_bf16 v[2:5], v[210:213], v[242:245], v[2:5]
	v_mfma_f32_16x16x32_bf16 v[50:53], v[202:205], v[218:221], v[50:53]
	s_setprio 0
	s_barrier
; #define STAGE(bufoff, gbase) do { _Pragma("unroll") for (int _i = 0; _i < 2; ++_i) \
;     __builtin_amdgcn_global_load_lds((const unsigned*)((const char*)(gbase) + voff[_i]), (__attribute__((address_space(3))) unsigned*)(lds + (bufoff) + ldsw + _i * 8192), 16, 0, 0); } while (0)
; #define LDA(dst, b, h) do { _Pragma("unroll") for (int m = 0; m < 4; ++m) _Pragma("unroll") for (int k = 0; k < 2; ++k) dst[m][k] = *(const __attribute__((address_space(3))) bf16x8*)(lds + SA(b, h) + aoff + m * 2048 + k * 1024); } while (0)
; #define LDB(dst, b, h) do { _Pragma("unroll") for (int n = 0; n < 2; ++n) _Pragma("unroll") for (int k = 0; k < 2; ++k) dst[n][k] = *(const __attribute__((address_space(3))) bf16x8*)(lds + SB(b, h) + boff + n * 2048 + k * 1024); } while (0)
; #define MMA(ai, bj, At_, Bt_) do { __builtin_amdgcn_s_setprio(1); \
;     _Pragma("unroll") for (int m = 0; m < 4; ++m) _Pragma("unroll") for (int n = 0; n < 2; ++n) _Pragma("unroll") for (int k = 0; k < 2; ++k) \
;       acc[ai][bj][m][n] = MFMA16(Bt_[n][k], At_[m][k], acc[ai][bj][m][n]); \
;     __builtin_amdgcn_s_setprio(0); } while (0)
; #define WAIT_V(n) asm volatile("s_waitcnt vmcnt(" #n ")" ::: "memory")
; #define WAIT_L(n) asm volatile("s_waitcnt lgkmcnt(" #n ")" ::: "memory")
; #define BAR __builtin_amdgcn_s_barrier()
; #define SCHED __builtin_amdgcn_sched_barrier(0)
; DI void gemm_phase(const GemmArgs& g, char* shm_c) {
;     ...
;       LDB(B0, 1, 0); LDB(B1, 1, 1); SCHED; LDA(At, 1, 0); STAGE(SA(0, 1), a2 + hstep);
;       WAIT_V(8); WAIT_L(0); BAR; MMA(0, 0, At, B0); MMA(0, 1, At, B1); BAR; SCHED;
;       LDA(At, 1, 1); STAGE(SB(1, 0), b3); STAGE(SB(1, 1), b3 + hstep); STAGE(SA(1, 0), a3);
;       WAIT_V(8); WAIT_L(0); BAR; MMA(1, 0, At, B0); MMA(1, 1, At, B1); BAR; SCHED;
;     }
	s_add_i32 s2, 0, 0x18000
	s_add_i32 s41, 0, 0x1c000
	v_add_u32_e32 v102, s2, v195
	v_add_u32_e32 v197, s41, v195
	ds_read_b128 v[58:61], v102
	ds_read_b128 v[86:89], v102 offset:1024
	ds_read_b128 v[90:93], v102 offset:2048
	ds_read_b128 v[102:105], v102 offset:3072
	ds_read_b128 v[198:201], v197
	ds_read_b128 v[202:205], v197 offset:1024
	ds_read_b128 v[206:209], v197 offset:2048
	ds_read_b128 v[210:213], v197 offset:3072
	s_add_u32 s24, s30, 0xb0000
	s_addc_u32 s25, s31, 0
	s_add_i32 m0, s49, 0x4000
	ds_read_b128 v[214:217], v196 offset:32768
	ds_read_b128 v[218:221], v196 offset:33792
	ds_read_b128 v[222:225], v196 offset:34816
	ds_read_b128 v[226:229], v196 offset:35840
	ds_read_b128 v[230:233], v196 offset:36864
	ds_read_b128 v[234:237], v196 offset:37888
	ds_read_b128 v[238:241], v196 offset:38912
	ds_read_b128 v[242:245], v196 offset:39936
	global_load_lds_dwordx4 v146, s[24:25]
	s_add_i32 m0, s49, 0x6000
	s_nop 0
	global_load_lds_dwordx4 v148, s[24:25]
	s_waitcnt vmcnt(8)
	s_waitcnt lgkmcnt(0)
	s_barrier
	s_setprio 1
	s_waitcnt lgkmcnt(0)
	v_mfma_f32_16x16x32_bf16 v[142:145], v[58:61], v[214:217], v[142:145]
	v_mfma_f32_16x16x32_bf16 v[138:141], v[90:93], v[214:217], v[138:141]
	v_mfma_f32_16x16x32_bf16 v[126:129], v[58:61], v[222:225], v[126:129]
	v_mfma_f32_16x16x32_bf16 v[122:125], v[90:93], v[222:225], v[122:125]
	v_mfma_f32_16x16x32_bf16 v[110:113], v[58:61], v[230:233], v[110:113]
	v_mfma_f32_16x16x32_bf16 v[106:109], v[90:93], v[230:233], v[106:109]
	v_mfma_f32_16x16x32_bf16 v[82:85], v[58:61], v[238:241], v[82:85]
	v_mfma_f32_16x16x32_bf16 v[78:81], v[90:93], v[238:241], v[78:81]
	v_mfma_f32_16x16x32_bf16 v[142:145], v[86:89], v[218:221], v[142:145]
	v_mfma_f32_16x16x32_bf16 v[138:141], v[102:105], v[218:221], v[138:141]
	v_mfma_f32_16x16x32_bf16 v[126:129], v[86:89], v[226:229], v[126:129]
	v_mfma_f32_16x16x32_bf16 v[122:125], v[102:105], v[226:229], v[122:125]
	v_mfma_f32_16x16x32_bf16 v[110:113], v[86:89], v[234:237], v[110:113]
	v_mfma_f32_16x16x32_bf16 v[106:109], v[102:105], v[234:237], v[106:109]
	v_mfma_f32_16x16x32_bf16 v[82:85], v[86:89], v[242:245], v[82:85]
	v_mfma_f32_16x16x32_bf16 v[78:81], v[102:105], v[242:245], v[78:81]
	s_setprio 0
	s_setprio 1
	v_mfma_f32_16x16x32_bf16 v[134:137], v[198:201], v[214:217], v[134:137]
	v_mfma_f32_16x16x32_bf16 v[130:133], v[206:209], v[214:217], v[130:133]
	v_mfma_f32_16x16x32_bf16 v[118:121], v[198:201], v[222:225], v[118:121]
	v_mfma_f32_16x16x32_bf16 v[114:117], v[206:209], v[222:225], v[114:117]
	v_mfma_f32_16x16x32_bf16 v[98:101], v[198:201], v[230:233], v[98:101]
	v_mfma_f32_16x16x32_bf16 v[94:97], v[206:209], v[230:233], v[94:97]
	v_mfma_f32_16x16x32_bf16 v[74:77], v[198:201], v[238:241], v[74:77]
	v_mfma_f32_16x16x32_bf16 v[70:73], v[206:209], v[238:241], v[70:73]
	v_mfma_f32_16x16x32_bf16 v[134:137], v[202:205], v[218:221], v[134:137]
	v_mfma_f32_16x16x32_bf16 v[130:133], v[210:213], v[218:221], v[130:133]
	v_mfma_f32_16x16x32_bf16 v[118:121], v[202:205], v[226:229], v[118:121]
	v_mfma_f32_16x16x32_bf16 v[114:117], v[210:213], v[226:229], v[114:117]
	v_mfma_f32_16x16x32_bf16 v[98:101], v[202:205], v[234:237], v[98:101]
	v_mfma_f32_16x16x32_bf16 v[94:97], v[210:213], v[234:237], v[94:97]
	v_mfma_f32_16x16x32_bf16 v[74:77], v[202:205], v[242:245], v[74:77]
	v_mfma_f32_16x16x32_bf16 v[70:73], v[210:213], v[242:245], v[70:73]
	s_setprio 0
	s_barrier
	s_add_i32 s2, s2, s36
	s_add_i32 m0, s2, 0xffffff80
	ds_read_b128 v[214:217], v196 offset:49152
	ds_read_b128 v[218:221], v196 offset:50176
	ds_read_b128 v[222:225], v196 offset:51200
	ds_read_b128 v[226:229], v196 offset:52224
	ds_read_b128 v[230:233], v196 offset:53248
	ds_read_b128 v[234:237], v196 offset:54272
	ds_read_b128 v[238:241], v196 offset:55296
	ds_read_b128 v[242:245], v196 offset:56320
	global_load_lds_dwordx4 v146, s[28:29] offset:128
	s_add_i32 m0, s2, 0x1f80
	s_add_u32 s24, s28, 0xb0080
	s_addc_u32 s25, s29, 0
	s_add_i32 s2, s41, s36
	global_load_lds_dwordx4 v148, s[28:29] offset:128
	s_mov_b32 m0, s2
	s_nop 0
	global_load_lds_dwordx4 v146, s[24:25]
	s_add_i32 m0, s2, 0x2000
	s_nop 0
	global_load_lds_dwordx4 v148, s[24:25]
	s_add_i32 m0, s49, 0x7f80
	s_nop 0
	global_load_lds_dwordx4 v146, s[30:31] offset:128
	s_add_i32 m0, s49, 0x9f80
	s_nop 0
	global_load_lds_dwordx4 v148, s[30:31] offset:128
	s_waitcnt vmcnt(8)
	s_waitcnt lgkmcnt(0)
	s_barrier
	s_setprio 1
	s_waitcnt lgkmcnt(0)
	v_mfma_f32_16x16x32_bf16 v[66:69], v[58:61], v[214:217], v[66:69]
	v_mfma_f32_16x16x32_bf16 v[62:65], v[90:93], v[214:217], v[62:65]
	v_mfma_f32_16x16x32_bf16 v[46:49], v[58:61], v[222:225], v[46:49]
	v_mfma_f32_16x16x32_bf16 v[42:45], v[90:93], v[222:225], v[42:45]
	v_mfma_f32_16x16x32_bf16 v[26:29], v[58:61], v[230:233], v[26:29]
	v_mfma_f32_16x16x32_bf16 v[18:21], v[90:93], v[230:233], v[18:21]
	v_mfma_f32_16x16x32_bf16 v[10:13], v[58:61], v[238:241], v[10:13]
	v_mfma_f32_16x16x32_bf16 v[6:9], v[90:93], v[238:241], v[6:9]
	v_mfma_f32_16x16x32_bf16 v[66:69], v[86:89], v[218:221], v[66:69]
	v_mfma_f32_16x16x32_bf16 v[62:65], v[102:105], v[218:221], v[62:65]
	v_mfma_f32_16x16x32_bf16 v[46:49], v[86:89], v[226:229], v[46:49]
	v_mfma_f32_16x16x32_bf16 v[42:45], v[102:105], v[226:229], v[42:45]
	v_mfma_f32_16x16x32_bf16 v[26:29], v[86:89], v[234:237], v[26:29]
	v_mfma_f32_16x16x32_bf16 v[18:21], v[102:105], v[234:237], v[18:21]
	v_mfma_f32_16x16x32_bf16 v[10:13], v[86:89], v[242:245], v[10:13]
	v_mfma_f32_16x16x32_bf16 v[6:9], v[102:105], v[242:245], v[6:9]
	s_setprio 0
	s_setprio 1
	v_mfma_f32_16x16x32_bf16 v[50:53], v[198:201], v[214:217], v[50:53]
	v_mfma_f32_16x16x32_bf16 v[58:61], v[202:205], v[218:221], v[50:53]
	v_mfma_f32_16x16x32_bf16 v[50:53], v[206:209], v[214:217], v[54:57]
	v_mfma_f32_16x16x32_bf16 v[38:41], v[198:201], v[222:225], v[38:41]
	v_mfma_f32_16x16x32_bf16 v[22:25], v[206:209], v[222:225], v[22:25]
	v_mfma_f32_16x16x32_bf16 v[34:37], v[198:201], v[230:233], v[34:37]
	v_mfma_f32_16x16x32_bf16 v[30:33], v[206:209], v[230:233], v[30:33]
	v_mfma_f32_16x16x32_bf16 v[14:17], v[198:201], v[238:241], v[14:17]
	v_mfma_f32_16x16x32_bf16 v[2:5], v[206:209], v[238:241], v[2:5]
	v_mfma_f32_16x16x32_bf16 v[54:57], v[210:213], v[218:221], v[50:53]
	v_mfma_f32_16x16x32_bf16 v[38:41], v[202:205], v[226:229], v[38:41]
	v_mfma_f32_16x16x32_bf16 v[22:25], v[210:213], v[226:229], v[22:25]
	v_mfma_f32_16x16x32_bf16 v[34:37], v[202:205], v[234:237], v[34:37]
	v_mfma_f32_16x16x32_bf16 v[30:33], v[210:213], v[234:237], v[30:33]
	v_mfma_f32_16x16x32_bf16 v[14:17], v[202:205], v[242:245], v[14:17]
	v_mfma_f32_16x16x32_bf16 v[2:5], v[210:213], v[242:245], v[2:5]
	s_setprio 0
	s_barrier
	s_add_i32 s48, s48, 2
	s_add_u32 s3, s3, 0x100
	s_addc_u32 s33, s33, 0
	s_cmp_gt_u32 s48, 41
	s_mov_b64 s[24:25], s[26:27]
	s_cbranch_scc0 .LBB0_1119
	s_and_b64 vcc, exec, s[12:13]
	s_cbranch_vccz .LBB0_1122
	s_barrier
